# flash loops: active waves issue the K/V LDS-DMA between the row-sum ds_bpermute and its wait (skipping waves still issue at the tail)
# speedup vs baseline: 1.0171x; 1.0075x over previous
; #define MFMA(a, b, c) __builtin_amdgcn_mfma_f32_32x32x16_bf16((a), (b), (c), 0, 0, 0)
;     ...
;   float mc = m * c2;
;   if (MODE == 2) mc = selbit ? mc : 1e30f;
;   const f32x2v c2v = {c2, c2}, mcv = {-mc, -mc};
;   f32x2v rs2 = {0.f, 0.f};
; #pragma unroll
;   for (int ks = 0; ks < 2; ++ks)
; #pragma unroll
;     for (int st = 0; st < 2; ++st) {
;       union { unsigned u[4]; bf16x8 v; } pf;
; #pragma unroll
;       for (int j = 0; j < 4; ++j) {
;         const int i0 = 8 * st + 2 * j;
;         f32x2v t = {S[ks][i0], S[ks][i0 + 1]};
;         t = __builtin_elementwise_fma(t, c2v, mcv);
;         f32x2v pv;
;         if (variant == 1) { pv = t; } else {
;         pv.x = __builtin_amdgcn_exp2f(t.x);
;         pv.y = __builtin_amdgcn_exp2f(t.y);
;         }
;         if (MODE != 0) {
;           if (need_mask) {
;             pv.x = (S[ks][i0] > -1e29f) ? pv.x : 0.f;
;             pv.y = (S[ks][i0 + 1] > -1e29f) ? pv.y : 0.f;
;           }
;         }
;         rs2 += pv;
;         pf.u[j] = __builtin_bit_cast(unsigned, __builtin_convertvector(pv, hwbf16x2));
;       }
; #pragma unroll
;       for (int d = 0; d < DV / 32; ++d) {
;         const char* vp = base + C::KBYTES + (d * 32 + lr) * C::VSTR + (ks * 32 + 16 * st + 4 * lh) * 2;
;         const s16x4 lo = *(const s16x4*)vp, hi = *(const s16x4*)(vp + 16);
;         const bf16x8 vf = __builtin_shufflevector(lo, hi, 0, 1, 2, 3, 4, 5, 6, 7);
;         O[d] = MFMA(vf, pf.v, O[d]);
;       }
;     }
.LBB0_362:
	s_cmp_eq_u64 s[8:9], 0
	s_cbranch_scc1 .Lfast_mla1
	v_mul_f32_e32 v104, 0xbe16c740, v104
	s_mov_b32 s12, 0x3e16c740
	v_pk_fma_f32 v[118:119], v[50:51], s[12:13], v[104:105] op_sel_hi:[1,0,0]
	v_cmp_lt_f32_e32 vcc, s33, v50
	v_exp_f32_e32 v118, v118
	v_exp_f32_e32 v119, v119
	v_cndmask_b32_e32 v50, 0, v118, vcc
	v_cmp_lt_f32_e32 vcc, s33, v51
	v_cndmask_b32_e64 v126, v118, v50, s[8:9]
	s_nop 0
	v_cndmask_b32_e32 v51, 0, v119, vcc
	v_cndmask_b32_e64 v127, v119, v51, s[8:9]
	v_pk_fma_f32 v[50:51], v[52:53], s[12:13], v[104:105] op_sel_hi:[1,0,0]
	v_cmp_lt_f32_e32 vcc, s33, v52
	v_exp_f32_e32 v50, v50
	v_exp_f32_e32 v51, v51
	v_cvt_pk_bf16_f32 v118, v126, v127
	v_cndmask_b32_e32 v52, 0, v50, vcc
	v_cmp_lt_f32_e32 vcc, s33, v53
	v_cndmask_b32_e64 v128, v50, v52, s[8:9]
	s_nop 0
	v_cndmask_b32_e32 v53, 0, v51, vcc
	v_cndmask_b32_e64 v129, v51, v53, s[8:9]
	v_pk_fma_f32 v[50:51], v[54:55], s[12:13], v[104:105] op_sel_hi:[1,0,0]
	v_cmp_lt_f32_e32 vcc, s33, v54
	v_exp_f32_e32 v50, v50
	v_exp_f32_e32 v51, v51
	v_cvt_pk_bf16_f32 v119, v128, v129
	v_cndmask_b32_e32 v52, 0, v50, vcc
	v_cmp_lt_f32_e32 vcc, s33, v55
	v_cndmask_b32_e64 v130, v50, v52, s[8:9]
	s_nop 0
	v_cndmask_b32_e32 v53, 0, v51, vcc
	v_cndmask_b32_e64 v131, v51, v53, s[8:9]
	v_pk_fma_f32 v[50:51], v[56:57], s[12:13], v[104:105] op_sel_hi:[1,0,0]
	v_cmp_lt_f32_e32 vcc, s33, v56
	v_exp_f32_e32 v50, v50
	v_exp_f32_e32 v51, v51
	v_cvt_pk_bf16_f32 v120, v130, v131
	v_cndmask_b32_e32 v52, 0, v50, vcc
	v_cmp_lt_f32_e32 vcc, s33, v57
	v_cndmask_b32_e64 v56, v50, v52, s[8:9]
	s_nop 0
	v_cndmask_b32_e32 v53, 0, v51, vcc
	v_cndmask_b32_e64 v57, v51, v53, s[8:9]
	v_cvt_pk_bf16_f32 v121, v56, v57
	v_cmp_lt_f32_e32 vcc, s33, v58
	s_waitcnt lgkmcnt(0)
	v_mfma_f32_32x32x16_bf16 v[18:33], v[216:219], v[118:121], v[18:33]
	s_waitcnt lgkmcnt(0)
	v_mfma_f32_32x32x16_bf16 v[2:17], v[220:223], v[118:121], v[2:17]
	v_add_f32_e64 v52, v126, 0
	v_add_f32_e64 v53, v127, 0
	v_add_f32_e64 v52, v128, v52
	v_add_f32_e64 v53, v129, v53
	v_add_f32_e64 v52, v130, v52
	v_add_f32_e64 v53, v131, v53
	v_pk_add_f32 v[118:119], v[56:57], v[52:53]
	v_pk_fma_f32 v[52:53], v[58:59], s[12:13], v[104:105] op_sel_hi:[1,0,0]
	s_nop 0
	v_exp_f32_e32 v52, v52
	v_exp_f32_e32 v53, v53
	v_cndmask_b32_e32 v54, 0, v52, vcc
	v_cmp_lt_f32_e32 vcc, s33, v59
	v_cndmask_b32_e64 v120, v52, v54, s[8:9]
	s_nop 0
	v_cndmask_b32_e32 v55, 0, v53, vcc
	v_cndmask_b32_e64 v121, v53, v55, s[8:9]
	v_pk_fma_f32 v[54:55], v[60:61], s[12:13], v[104:105] op_sel_hi:[1,0,0]
	v_cmp_lt_f32_e32 vcc, s33, v60
	v_exp_f32_e32 v53, v54
	v_exp_f32_e32 v54, v55
	v_cvt_pk_bf16_f32 v52, v120, v121
	v_cndmask_b32_e32 v55, 0, v53, vcc
	v_cmp_lt_f32_e32 vcc, s33, v61
	v_cndmask_b32_e64 v60, v53, v55, s[8:9]
	s_nop 0
	v_cndmask_b32_e32 v56, 0, v54, vcc
	v_cndmask_b32_e64 v61, v54, v56, s[8:9]
	v_pk_fma_f32 v[54:55], v[62:63], s[12:13], v[104:105] op_sel_hi:[1,0,0]
	v_cmp_lt_f32_e32 vcc, s33, v62
	v_exp_f32_e32 v54, v54
	v_exp_f32_e32 v55, v55
	v_cvt_pk_bf16_f32 v53, v60, v61
	v_cndmask_b32_e32 v56, 0, v54, vcc
	v_cmp_lt_f32_e32 vcc, s33, v63
	v_cndmask_b32_e64 v62, v54, v56, s[8:9]
	s_nop 0
	v_cndmask_b32_e32 v57, 0, v55, vcc
	v_cndmask_b32_e64 v63, v55, v57, s[8:9]
	v_pk_fma_f32 v[56:57], v[64:65], s[12:13], v[104:105] op_sel_hi:[1,0,0]
	v_cmp_lt_f32_e32 vcc, s33, v64
	v_exp_f32_e32 v55, v56
	v_exp_f32_e32 v56, v57
	v_cvt_pk_bf16_f32 v54, v62, v63
	v_cndmask_b32_e32 v57, 0, v55, vcc
	v_cmp_lt_f32_e32 vcc, s33, v65
	v_cndmask_b32_e64 v64, v55, v57, s[8:9]
	s_nop 0
	v_cndmask_b32_e32 v58, 0, v56, vcc
	v_cndmask_b32_e64 v65, v56, v58, s[8:9]
	v_cvt_pk_bf16_f32 v55, v64, v65
	v_cmp_lt_f32_e32 vcc, s33, v34
	s_nop 0
	v_mfma_f32_32x32x16_bf16 v[18:33], v[224:227], v[52:55], v[18:33]
	s_waitcnt lgkmcnt(0)
	v_mfma_f32_32x32x16_bf16 v[2:17], v[228:231], v[52:55], v[2:17]
	v_fma_f32 v54, v34, s12, v104
	v_fma_f32 v55, v35, s12, v104
	v_fma_f32 v56, v36, s12, v104
	v_fma_f32 v57, v37, s12, v104
	v_exp_f32_e32 v54, v54
	v_exp_f32_e32 v55, v55
	v_pk_add_f32 v[52:53], v[120:121], v[118:119]
	v_cndmask_b32_e32 v34, 0, v54, vcc
	v_cmp_lt_f32_e32 vcc, s33, v35
	v_pk_add_f32 v[52:53], v[60:61], v[52:53]
	v_cndmask_b32_e64 v54, v54, v34, s[8:9]
	v_cndmask_b32_e32 v35, 0, v55, vcc
	v_cndmask_b32_e64 v55, v55, v35, s[8:9]
	v_exp_f32_e32 v35, v56
	v_exp_f32_e32 v56, v57
	v_cmp_lt_f32_e32 vcc, s33, v36
	v_cvt_pk_bf16_f32 v34, v54, v55
	v_pk_add_f32 v[52:53], v[62:63], v[52:53]
	v_cndmask_b32_e32 v36, 0, v35, vcc
	v_cmp_lt_f32_e32 vcc, s33, v37
	v_pk_add_f32 v[52:53], v[64:65], v[52:53]
	s_nop 0
	v_cndmask_b32_e32 v37, 0, v56, vcc
	v_cndmask_b32_e64 v57, v56, v37, s[8:9]
	v_cndmask_b32_e64 v56, v35, v36, s[8:9]
	v_pk_fma_f32 v[36:37], v[38:39], s[12:13], v[104:105] op_sel_hi:[1,0,0]
	v_cmp_lt_f32_e32 vcc, s33, v38
	v_exp_f32_e32 v36, v36
	v_exp_f32_e32 v37, v37
	v_cvt_pk_bf16_f32 v35, v56, v57
	v_cndmask_b32_e32 v38, 0, v36, vcc
	v_cmp_lt_f32_e32 vcc, s33, v39
	v_cndmask_b32_e64 v58, v36, v38, s[8:9]
	s_nop 0
	v_cndmask_b32_e32 v39, 0, v37, vcc
	v_cndmask_b32_e64 v59, v37, v39, s[8:9]
	v_pk_fma_f32 v[38:39], v[40:41], s[12:13], v[104:105] op_sel_hi:[1,0,0]
	v_cmp_lt_f32_e32 vcc, s33, v40
	v_exp_f32_e32 v37, v38
	v_exp_f32_e32 v38, v39
	v_cvt_pk_bf16_f32 v36, v58, v59
	v_cndmask_b32_e32 v39, 0, v37, vcc
	v_cmp_lt_f32_e32 vcc, s33, v41
	v_cndmask_b32_e64 v60, v37, v39, s[8:9]
	s_nop 0
	v_cndmask_b32_e32 v40, 0, v38, vcc
	v_cndmask_b32_e64 v61, v38, v40, s[8:9]
	v_cvt_pk_bf16_f32 v37, v60, v61
	v_cmp_lt_f32_e32 vcc, s33, v42
	s_waitcnt lgkmcnt(0)
	v_mfma_f32_32x32x16_bf16 v[18:33], v[232:235], v[34:37], v[18:33]
	s_waitcnt lgkmcnt(0)
; #define MFMA(a, b, c) __builtin_amdgcn_mfma_f32_32x32x16_bf16((a), (b), (c), 0, 0, 0)
;     ...
; #pragma unroll
;       for (int d = 0; d < DV / 32; ++d) {
;         const char* vp = base + C::KBYTES + (d * 32 + lr) * C::VSTR + (ks * 32 + 16 * st + 4 * lh) * 2;
;         const s16x4 lo = *(const s16x4*)vp, hi = *(const s16x4*)(vp + 16);
;         const bf16x8 vf = __builtin_shufflevector(lo, hi, 0, 1, 2, 3, 4, 5, 6, 7);
;         O[d] = MFMA(vf, pf.v, O[d]);
;       }
;     }
;   float rs = rs2.x + rs2.y;
;   rs += __shfl_xor(rs, 32);
;   l += rs;
;     ...
;     if (t + NST - 1 < ntile) {
;       const int sn = (stage == 0) ? NST - 1 : stage - 1;
;       FA_ISSUE(t + NST - 1, sn)
;     }
	v_mfma_f32_32x32x16_bf16 v[2:17], v[236:239], v[34:37], v[2:17]
	v_add_f32_e64 v34, v54, v52
	v_add_f32_e64 v35, v55, v53
	v_add_f32_e64 v34, v56, v34
	v_add_f32_e64 v35, v57, v35
	v_add_f32_e64 v34, v58, v34
	v_add_f32_e64 v35, v59, v35
	v_pk_add_f32 v[52:53], v[60:61], v[34:35]
	v_pk_fma_f32 v[34:35], v[42:43], s[12:13], v[104:105] op_sel_hi:[1,0,0]
	s_nop 0
	v_exp_f32_e32 v34, v34
	v_exp_f32_e32 v35, v35
	v_cndmask_b32_e32 v36, 0, v34, vcc
	v_cmp_lt_f32_e32 vcc, s33, v43
	v_cndmask_b32_e64 v42, v34, v36, s[8:9]
	s_nop 0
	v_cndmask_b32_e32 v37, 0, v35, vcc
	v_cndmask_b32_e64 v43, v35, v37, s[8:9]
	v_pk_fma_f32 v[36:37], v[44:45], s[12:13], v[104:105] op_sel_hi:[1,0,0]
	v_cmp_lt_f32_e32 vcc, s33, v44
	v_exp_f32_e32 v35, v36
	v_exp_f32_e32 v36, v37
	v_cvt_pk_bf16_f32 v34, v42, v43
	v_cndmask_b32_e32 v37, 0, v35, vcc
	v_cmp_lt_f32_e32 vcc, s33, v45
	v_cndmask_b32_e64 v44, v35, v37, s[8:9]
	s_nop 0
	v_cndmask_b32_e32 v38, 0, v36, vcc
	v_cndmask_b32_e64 v45, v36, v38, s[8:9]
	v_pk_fma_f32 v[36:37], v[46:47], s[12:13], v[104:105] op_sel_hi:[1,0,0]
	v_cmp_lt_f32_e32 vcc, s33, v46
	v_exp_f32_e32 v36, v36
	v_exp_f32_e32 v37, v37
	v_cvt_pk_bf16_f32 v35, v44, v45
	v_cndmask_b32_e32 v38, 0, v36, vcc
	v_cmp_lt_f32_e32 vcc, s33, v47
	v_cndmask_b32_e64 v46, v36, v38, s[8:9]
	s_nop 0
	v_cndmask_b32_e32 v39, 0, v37, vcc
	v_cndmask_b32_e64 v47, v37, v39, s[8:9]
	v_pk_fma_f32 v[38:39], v[48:49], s[12:13], v[104:105] op_sel_hi:[1,0,0]
	v_cmp_lt_f32_e32 vcc, s33, v48
	v_exp_f32_e32 v37, v38
	v_exp_f32_e32 v38, v39
	v_cvt_pk_bf16_f32 v36, v46, v47
	v_cndmask_b32_e32 v39, 0, v37, vcc
	v_cmp_lt_f32_e32 vcc, s33, v49
	v_cndmask_b32_e64 v48, v37, v39, s[8:9]
	s_nop 0
	v_cndmask_b32_e32 v40, 0, v38, vcc
	v_cndmask_b32_e64 v49, v38, v40, s[8:9]
	v_cvt_pk_bf16_f32 v37, v48, v49
	s_waitcnt lgkmcnt(0)
	s_nop 0
	v_mfma_f32_32x32x16_bf16 v[18:33], v[240:243], v[34:37], v[18:33]
	s_waitcnt lgkmcnt(0)
	v_mfma_f32_32x32x16_bf16 v[2:17], v[244:247], v[34:37], v[2:17]
	v_add_f32_e64 v34, v42, v52
	v_add_f32_e64 v35, v43, v53
	v_add_f32_e64 v34, v44, v34
	v_add_f32_e64 v35, v45, v35
	v_add_f32_e64 v34, v46, v34
	v_add_f32_e64 v35, v47, v35
	v_pk_add_f32 v[34:35], v[48:49], v[34:35]
	s_nop 0
	v_add_f32_e32 v34, v34, v35
	ds_bpermute_b32 v35, v117, v34
	s_cmp_ge_u32 s16, s19
	s_cbranch_scc1 .Ldma_m_mla1
	s_add_i32 s98, s6, 0xffffa800
	s_cmp_lg_u32 s22, 0
	s_cselect_b32 s98, s98, 0x10800
	s_add_i32 s98, s98, 0
	v_add_u32_e32 v247, s98, v107
	s_nop 0
	v_readfirstlane_b32 s99, v247
	v_add_u32_e32 v247, s98, v93
	s_mov_b32 m0, s99
	v_readfirstlane_b32 s99, v247
	v_add_u32_e32 v247, s98, v108
	global_load_lds_dwordx4 v[102:103], off
	s_mov_b32 m0, s99
	v_readfirstlane_b32 s98, v247
	global_load_lds_dwordx4 v[100:101], off
	s_mov_b32 m0, s98
	s_nop 0
	global_load_lds_dwordx4 v[98:99], off
.Ldma_m_mla1:
	s_waitcnt lgkmcnt(0)
	v_add_f32_e32 v34, v34, v35
	v_add_f32_e32 v109, v109, v34
	s_or_b64 exec, exec, s[10:11]
	s_branch .Ldma_skip_mla1
; #define MFMA(a, b, c) __builtin_amdgcn_mfma_f32_32x32x16_bf16((a), (b), (c), 0, 0, 0)
;     ...
;   const f32x2v c2v = {c2, c2}, mcv = {-mc, -mc};
;   f32x2v rs2 = {0.f, 0.f};
; #pragma unroll
;   for (int ks = 0; ks < 2; ++ks)
; #pragma unroll
;     for (int st = 0; st < 2; ++st) {
;       union { unsigned u[4]; bf16x8 v; } pf;
; #pragma unroll
;       for (int j = 0; j < 4; ++j) {
;         const int i0 = 8 * st + 2 * j;
;         f32x2v t = {S[ks][i0], S[ks][i0 + 1]};
;         t = __builtin_elementwise_fma(t, c2v, mcv);
;         f32x2v pv;
;         if (variant == 1) { pv = t; } else {
;         pv.x = __builtin_amdgcn_exp2f(t.x);
;         pv.y = __builtin_amdgcn_exp2f(t.y);
;         }
;         if (MODE != 0) {
;           if (need_mask) {
;             pv.x = (S[ks][i0] > -1e29f) ? pv.x : 0.f;
;             pv.y = (S[ks][i0 + 1] > -1e29f) ? pv.y : 0.f;
;           }
;         }
;         rs2 += pv;
;         pf.u[j] = __builtin_bit_cast(unsigned, __builtin_convertvector(pv, hwbf16x2));
;       }
; #pragma unroll
;       for (int d = 0; d < DV / 32; ++d) {
;         const char* vp = base + C::KBYTES + (d * 32 + lr) * C::VSTR + (ks * 32 + 16 * st + 4 * lh) * 2;
;         const s16x4 lo = *(const s16x4*)vp, hi = *(const s16x4*)(vp + 16);
;         const bf16x8 vf = __builtin_shufflevector(lo, hi, 0, 1, 2, 3, 4, 5, 6, 7);
;         O[d] = MFMA(vf, pf.v, O[d]);
;       }
;     }
;   float rs = rs2.x + rs2.y;
;   rs += __shfl_xor(rs, 32);
.Lfast_mla1:
	v_mul_f32_e32 v104, 0xbe16c740, v104
	s_mov_b32 s12, 0x3e16c740
	v_pk_fma_f32 v[118:119], v[50:51], s[12:13], v[104:105] op_sel_hi:[1,0,0]
	v_exp_f32_e32 v126, v118
	v_exp_f32_e32 v127, v119
	v_pk_fma_f32 v[50:51], v[52:53], s[12:13], v[104:105] op_sel_hi:[1,0,0]
	v_exp_f32_e32 v128, v50
	v_exp_f32_e32 v129, v51
	v_cvt_pk_bf16_f32 v118, v126, v127
	v_pk_fma_f32 v[50:51], v[54:55], s[12:13], v[104:105] op_sel_hi:[1,0,0]
	v_exp_f32_e32 v130, v50
	v_exp_f32_e32 v131, v51
	v_cvt_pk_bf16_f32 v119, v128, v129
	v_pk_fma_f32 v[50:51], v[56:57], s[12:13], v[104:105] op_sel_hi:[1,0,0]
	v_exp_f32_e32 v56, v50
	v_exp_f32_e32 v57, v51
	v_cvt_pk_bf16_f32 v120, v130, v131
	v_cvt_pk_bf16_f32 v121, v56, v57
	s_waitcnt lgkmcnt(0)
	s_nop 0
	v_mfma_f32_32x32x16_bf16 v[18:33], v[216:219], v[118:121], v[18:33]
	s_waitcnt lgkmcnt(0)
	v_mfma_f32_32x32x16_bf16 v[2:17], v[220:223], v[118:121], v[2:17]
	v_add_f32_e64 v52, v126, 0
	v_add_f32_e64 v53, v127, 0
	v_add_f32_e64 v52, v128, v52
	v_add_f32_e64 v53, v129, v53
	v_add_f32_e64 v52, v130, v52
	v_add_f32_e64 v53, v131, v53
	v_pk_add_f32 v[118:119], v[56:57], v[52:53]
	v_pk_fma_f32 v[52:53], v[58:59], s[12:13], v[104:105] op_sel_hi:[1,0,0]
	v_exp_f32_e32 v120, v52
	v_exp_f32_e32 v121, v53
	v_pk_fma_f32 v[54:55], v[60:61], s[12:13], v[104:105] op_sel_hi:[1,0,0]
	v_exp_f32_e32 v60, v54
	v_exp_f32_e32 v61, v55
	v_cvt_pk_bf16_f32 v52, v120, v121
	v_pk_fma_f32 v[54:55], v[62:63], s[12:13], v[104:105] op_sel_hi:[1,0,0]
	v_exp_f32_e32 v62, v54
	v_exp_f32_e32 v63, v55
	v_cvt_pk_bf16_f32 v53, v60, v61
	v_pk_fma_f32 v[56:57], v[64:65], s[12:13], v[104:105] op_sel_hi:[1,0,0]
	v_exp_f32_e32 v64, v56
	v_exp_f32_e32 v65, v57
	v_cvt_pk_bf16_f32 v54, v62, v63
	v_cvt_pk_bf16_f32 v55, v64, v65
	s_nop 1
	v_mfma_f32_32x32x16_bf16 v[18:33], v[224:227], v[52:55], v[18:33]
	s_waitcnt lgkmcnt(0)
	v_mfma_f32_32x32x16_bf16 v[2:17], v[228:231], v[52:55], v[2:17]
	v_fma_f32 v54, v34, s12, v104
	v_fma_f32 v55, v35, s12, v104
	v_fma_f32 v56, v36, s12, v104
	v_fma_f32 v57, v37, s12, v104
	v_exp_f32_e32 v54, v54
	v_exp_f32_e32 v55, v55
	v_pk_add_f32 v[52:53], v[120:121], v[118:119]
	v_pk_add_f32 v[52:53], v[60:61], v[52:53]
	v_exp_f32_e32 v56, v56
	v_exp_f32_e32 v57, v57
	v_cvt_pk_bf16_f32 v34, v54, v55
	v_pk_add_f32 v[52:53], v[62:63], v[52:53]
	v_pk_add_f32 v[52:53], v[64:65], v[52:53]
	v_pk_fma_f32 v[36:37], v[38:39], s[12:13], v[104:105] op_sel_hi:[1,0,0]
	v_exp_f32_e32 v58, v36
	v_exp_f32_e32 v59, v37
	v_cvt_pk_bf16_f32 v35, v56, v57
	v_pk_fma_f32 v[38:39], v[40:41], s[12:13], v[104:105] op_sel_hi:[1,0,0]
	v_exp_f32_e32 v60, v38
	v_exp_f32_e32 v61, v39
	v_cvt_pk_bf16_f32 v36, v58, v59
	v_cvt_pk_bf16_f32 v37, v60, v61
	s_waitcnt lgkmcnt(0)
	s_nop 0
	v_mfma_f32_32x32x16_bf16 v[18:33], v[232:235], v[34:37], v[18:33]
	s_waitcnt lgkmcnt(0)
	v_mfma_f32_32x32x16_bf16 v[2:17], v[236:239], v[34:37], v[2:17]
	v_add_f32_e64 v34, v54, v52
	v_add_f32_e64 v35, v55, v53
	v_add_f32_e64 v34, v56, v34
	v_add_f32_e64 v35, v57, v35
	v_add_f32_e64 v34, v58, v34
	v_add_f32_e64 v35, v59, v35
	v_pk_add_f32 v[52:53], v[60:61], v[34:35]
	v_pk_fma_f32 v[34:35], v[42:43], s[12:13], v[104:105] op_sel_hi:[1,0,0]
	v_exp_f32_e32 v42, v34
	v_exp_f32_e32 v43, v35
	v_pk_fma_f32 v[36:37], v[44:45], s[12:13], v[104:105] op_sel_hi:[1,0,0]
	v_exp_f32_e32 v44, v36
	v_exp_f32_e32 v45, v37
	v_cvt_pk_bf16_f32 v34, v42, v43
	v_pk_fma_f32 v[36:37], v[46:47], s[12:13], v[104:105] op_sel_hi:[1,0,0]
	v_exp_f32_e32 v46, v36
	v_exp_f32_e32 v47, v37
	v_cvt_pk_bf16_f32 v35, v44, v45
	v_pk_fma_f32 v[38:39], v[48:49], s[12:13], v[104:105] op_sel_hi:[1,0,0]
	v_exp_f32_e32 v48, v38
	v_exp_f32_e32 v49, v39
	v_cvt_pk_bf16_f32 v36, v46, v47
	v_cvt_pk_bf16_f32 v37, v48, v49
	s_waitcnt lgkmcnt(0)
	s_nop 0
	v_mfma_f32_32x32x16_bf16 v[18:33], v[240:243], v[34:37], v[18:33]
	s_waitcnt lgkmcnt(0)
	v_mfma_f32_32x32x16_bf16 v[2:17], v[244:247], v[34:37], v[2:17]
	v_add_f32_e64 v34, v42, v52
	v_add_f32_e64 v35, v43, v53
	v_add_f32_e64 v34, v44, v34
	v_add_f32_e64 v35, v45, v35
	v_add_f32_e64 v34, v46, v34
	v_add_f32_e64 v35, v47, v35
	v_pk_add_f32 v[34:35], v[48:49], v[34:35]
	v_add_f32_e32 v34, v34, v35
	ds_bpermute_b32 v35, v117, v34
	s_cmp_ge_u32 s16, s19
	s_cbranch_scc1 .Ldma_f_mla1
	s_add_i32 s98, s6, 0xffffa800
	s_cmp_lg_u32 s22, 0
	s_cselect_b32 s98, s98, 0x10800
	s_add_i32 s98, s98, 0
	v_add_u32_e32 v247, s98, v107
	s_nop 0
	v_readfirstlane_b32 s99, v247
	v_add_u32_e32 v247, s98, v93
	s_mov_b32 m0, s99
	v_readfirstlane_b32 s99, v247
	v_add_u32_e32 v247, s98, v108
	global_load_lds_dwordx4 v[102:103], off
	s_mov_b32 m0, s99
	v_readfirstlane_b32 s98, v247
	global_load_lds_dwordx4 v[100:101], off
	s_mov_b32 m0, s98
	s_nop 0
	global_load_lds_dwordx4 v[98:99], off

; #define MFMA(a, b, c) __builtin_amdgcn_mfma_f32_32x32x16_bf16((a), (b), (c), 0, 0, 0)
;     ...
;   float mc = m * c2;
;   if (MODE == 2) mc = selbit ? mc : 1e30f;
;   const f32x2v c2v = {c2, c2}, mcv = {-mc, -mc};
;   f32x2v rs2 = {0.f, 0.f};
; #pragma unroll
;   for (int ks = 0; ks < 2; ++ks)
; #pragma unroll
;     for (int st = 0; st < 2; ++st) {
;       union { unsigned u[4]; bf16x8 v; } pf;
; #pragma unroll
;       for (int j = 0; j < 4; ++j) {
;         const int i0 = 8 * st + 2 * j;
;         f32x2v t = {S[ks][i0], S[ks][i0 + 1]};
;         t = __builtin_elementwise_fma(t, c2v, mcv);
;         f32x2v pv;
;         if (variant == 1) { pv = t; } else {
;         pv.x = __builtin_amdgcn_exp2f(t.x);
;         pv.y = __builtin_amdgcn_exp2f(t.y);
;         }
;         if (MODE != 0) {
;           if (need_mask) {
;             pv.x = (S[ks][i0] > -1e29f) ? pv.x : 0.f;
;             pv.y = (S[ks][i0 + 1] > -1e29f) ? pv.y : 0.f;
;           }
;         }
;         rs2 += pv;
;         pf.u[j] = __builtin_bit_cast(unsigned, __builtin_convertvector(pv, hwbf16x2));
;       }
; #pragma unroll
;       for (int d = 0; d < DV / 32; ++d) {
;         const char* vp = base + C::KBYTES + (d * 32 + lr) * C::VSTR + (ks * 32 + 16 * st + 4 * lh) * 2;
;         const s16x4 lo = *(const s16x4*)vp, hi = *(const s16x4*)(vp + 16);
;         const bf16x8 vf = __builtin_shufflevector(lo, hi, 0, 1, 2, 3, 4, 5, 6, 7);
;         O[d] = MFMA(vf, pf.v, O[d]);
;       }
;     }
.LBB0_424:
	s_cmp_eq_u64 s[8:9], 0
	s_cbranch_scc1 .Lfast_sel1
	v_mul_f32_e32 v110, 0xbe38aa3b, v110
	v_cndmask_b32_e64 v110, v208, v110, s[10:11]
	v_pk_fma_f32 v[120:121], v[82:83], s[96:97], v[110:111] op_sel_hi:[1,0,0]
	v_cmp_lt_f32_e32 vcc, s33, v82
	v_exp_f32_e32 v119, v120
	v_exp_f32_e32 v120, v121
	v_cndmask_b32_e32 v82, 0, v119, vcc
	v_cmp_lt_f32_e32 vcc, s33, v83
	v_cndmask_b32_e64 v128, v119, v82, s[8:9]
	s_nop 0
	v_cndmask_b32_e32 v83, 0, v120, vcc
	v_cndmask_b32_e64 v129, v120, v83, s[8:9]
	v_pk_fma_f32 v[82:83], v[84:85], s[96:97], v[110:111] op_sel_hi:[1,0,0]
	v_cmp_lt_f32_e32 vcc, s33, v84
	v_exp_f32_e32 v82, v82
	v_exp_f32_e32 v83, v83
	v_cvt_pk_bf16_f32 v120, v128, v129
	v_cndmask_b32_e32 v84, 0, v82, vcc
	v_cmp_lt_f32_e32 vcc, s33, v85
	v_cndmask_b32_e64 v152, v82, v84, s[8:9]
	s_nop 0
	v_cndmask_b32_e32 v85, 0, v83, vcc
	v_cndmask_b32_e64 v153, v83, v85, s[8:9]
	v_pk_fma_f32 v[82:83], v[86:87], s[96:97], v[110:111] op_sel_hi:[1,0,0]
	v_cmp_lt_f32_e32 vcc, s33, v86
	v_exp_f32_e32 v82, v82
	v_exp_f32_e32 v83, v83
	v_cvt_pk_bf16_f32 v121, v152, v153
	v_cndmask_b32_e32 v84, 0, v82, vcc
	v_cmp_lt_f32_e32 vcc, s33, v87
	v_cndmask_b32_e64 v154, v82, v84, s[8:9]
	s_nop 0
	v_cndmask_b32_e32 v85, 0, v83, vcc
	v_cndmask_b32_e64 v155, v83, v85, s[8:9]
	v_pk_fma_f32 v[82:83], v[88:89], s[96:97], v[110:111] op_sel_hi:[1,0,0]
	v_cmp_lt_f32_e32 vcc, s33, v88
	v_exp_f32_e32 v82, v82
	v_exp_f32_e32 v83, v83
	v_cvt_pk_bf16_f32 v122, v154, v155
	v_cndmask_b32_e32 v84, 0, v82, vcc
	v_cmp_lt_f32_e32 vcc, s33, v89
	v_cndmask_b32_e64 v88, v82, v84, s[8:9]
	s_nop 0
	v_cndmask_b32_e32 v85, 0, v83, vcc
	v_cndmask_b32_e64 v89, v83, v85, s[8:9]
	s_nop 0
	s_nop 0
	s_nop 0
	s_nop 0
	v_cvt_pk_bf16_f32 v123, v88, v89
	s_nop 0
	v_cmp_lt_f32_e32 vcc, s33, v90
	s_waitcnt lgkmcnt(0)
	v_mfma_f32_32x32x16_bf16 v[50:65], v[216:219], v[120:123], v[50:65]
	s_nop 0
	s_waitcnt lgkmcnt(0)
	v_mfma_f32_32x32x16_bf16 v[34:49], v[220:223], v[120:123], v[34:49]
	v_add_f32_e64 v84, v128, 0
	v_add_f32_e64 v85, v129, 0
	v_add_f32_e64 v84, v152, v84
	v_add_f32_e64 v85, v153, v85
	v_add_f32_e64 v84, v154, v84
	v_add_f32_e64 v85, v155, v85
	v_pk_add_f32 v[120:121], v[88:89], v[84:85]
	v_pk_fma_f32 v[84:85], v[90:91], s[96:97], v[110:111] op_sel_hi:[1,0,0]
	s_nop 0
	v_exp_f32_e32 v84, v84
	v_exp_f32_e32 v85, v85
	v_cndmask_b32_e32 v86, 0, v84, vcc
	v_cmp_lt_f32_e32 vcc, s33, v91
	v_cndmask_b32_e64 v122, v84, v86, s[8:9]
	s_nop 0
	v_cndmask_b32_e32 v87, 0, v85, vcc
	v_cndmask_b32_e64 v123, v85, v87, s[8:9]
	v_pk_fma_f32 v[86:87], v[92:93], s[96:97], v[110:111] op_sel_hi:[1,0,0]
	v_cmp_lt_f32_e32 vcc, s33, v92
	v_exp_f32_e32 v85, v86
	v_exp_f32_e32 v86, v87
	v_cvt_pk_bf16_f32 v84, v122, v123
	v_cndmask_b32_e32 v87, 0, v85, vcc
	v_cmp_lt_f32_e32 vcc, s33, v93
	v_cndmask_b32_e64 v92, v85, v87, s[8:9]
	s_nop 0
	v_cndmask_b32_e32 v88, 0, v86, vcc
	v_cndmask_b32_e64 v93, v86, v88, s[8:9]
	v_pk_fma_f32 v[86:87], v[94:95], s[96:97], v[110:111] op_sel_hi:[1,0,0]
	v_cmp_lt_f32_e32 vcc, s33, v94
	v_exp_f32_e32 v86, v86
	v_exp_f32_e32 v87, v87
	v_cvt_pk_bf16_f32 v85, v92, v93
	v_cndmask_b32_e32 v88, 0, v86, vcc
	v_cmp_lt_f32_e32 vcc, s33, v95
	v_cndmask_b32_e64 v94, v86, v88, s[8:9]
	s_nop 0
	v_cndmask_b32_e32 v89, 0, v87, vcc
	v_cndmask_b32_e64 v95, v87, v89, s[8:9]
	v_pk_fma_f32 v[88:89], v[96:97], s[96:97], v[110:111] op_sel_hi:[1,0,0]
	v_cmp_lt_f32_e32 vcc, s33, v96
	v_exp_f32_e32 v87, v88
	v_exp_f32_e32 v88, v89
	v_cvt_pk_bf16_f32 v86, v94, v95
	v_cndmask_b32_e32 v89, 0, v87, vcc
	v_cmp_lt_f32_e32 vcc, s33, v97
	v_cndmask_b32_e64 v96, v87, v89, s[8:9]
	s_nop 0
	v_cndmask_b32_e32 v90, 0, v88, vcc
	v_cndmask_b32_e64 v97, v88, v90, s[8:9]
	s_nop 0
	v_cvt_pk_bf16_f32 v87, v96, v97
	v_cmp_lt_f32_e32 vcc, s33, v66
	s_nop 0
	v_mfma_f32_32x32x16_bf16 v[50:65], v[224:227], v[84:87], v[50:65]
	s_waitcnt lgkmcnt(0)
	v_mfma_f32_32x32x16_bf16 v[34:49], v[228:231], v[84:87], v[34:49]
	v_fma_f32 v86, v66, s96, v110
	v_fma_f32 v87, v67, s96, v110
	v_fma_f32 v88, v68, s96, v110
	v_fma_f32 v89, v69, s96, v110
	v_exp_f32_e32 v86, v86
	v_exp_f32_e32 v87, v87
	v_pk_add_f32 v[84:85], v[122:123], v[120:121]
	v_cndmask_b32_e32 v66, 0, v86, vcc
	v_cmp_lt_f32_e32 vcc, s33, v67
	v_pk_add_f32 v[84:85], v[92:93], v[84:85]
	v_cndmask_b32_e64 v86, v86, v66, s[8:9]
	v_cndmask_b32_e32 v67, 0, v87, vcc
	v_cndmask_b32_e64 v87, v87, v67, s[8:9]
	v_exp_f32_e32 v67, v88
	v_exp_f32_e32 v88, v89
	v_cmp_lt_f32_e32 vcc, s33, v68
	v_cvt_pk_bf16_f32 v66, v86, v87
	v_pk_add_f32 v[84:85], v[94:95], v[84:85]
	v_cndmask_b32_e32 v68, 0, v67, vcc
	v_cmp_lt_f32_e32 vcc, s33, v69
	v_pk_add_f32 v[84:85], v[96:97], v[84:85]
	s_nop 0
	v_cndmask_b32_e32 v69, 0, v88, vcc
	v_cndmask_b32_e64 v89, v88, v69, s[8:9]
	v_cndmask_b32_e64 v88, v67, v68, s[8:9]
	v_pk_fma_f32 v[68:69], v[70:71], s[96:97], v[110:111] op_sel_hi:[1,0,0]
	v_cmp_lt_f32_e32 vcc, s33, v70
	v_exp_f32_e32 v68, v68
	v_exp_f32_e32 v69, v69
	v_cvt_pk_bf16_f32 v67, v88, v89
	v_cndmask_b32_e32 v70, 0, v68, vcc
	v_cmp_lt_f32_e32 vcc, s33, v71
	v_cndmask_b32_e64 v90, v68, v70, s[8:9]
	s_nop 0
	v_cndmask_b32_e32 v71, 0, v69, vcc
	v_cndmask_b32_e64 v91, v69, v71, s[8:9]
	v_pk_fma_f32 v[70:71], v[72:73], s[96:97], v[110:111] op_sel_hi:[1,0,0]
	v_cmp_lt_f32_e32 vcc, s33, v72
	v_exp_f32_e32 v69, v70
	v_exp_f32_e32 v70, v71
	v_cvt_pk_bf16_f32 v68, v90, v91
	v_cndmask_b32_e32 v71, 0, v69, vcc
	v_cmp_lt_f32_e32 vcc, s33, v73
	v_cndmask_b32_e64 v92, v69, v71, s[8:9]
	s_nop 0
	v_cndmask_b32_e32 v72, 0, v70, vcc
	v_cndmask_b32_e64 v93, v70, v72, s[8:9]
	s_nop 0
	v_cvt_pk_bf16_f32 v69, v92, v93
	v_cmp_lt_f32_e32 vcc, s33, v74
	s_waitcnt lgkmcnt(0)
; #define MFMA(a, b, c) __builtin_amdgcn_mfma_f32_32x32x16_bf16((a), (b), (c), 0, 0, 0)
;     ...
; #pragma unroll
;       for (int d = 0; d < DV / 32; ++d) {
;         const char* vp = base + C::KBYTES + (d * 32 + lr) * C::VSTR + (ks * 32 + 16 * st + 4 * lh) * 2;
;         const s16x4 lo = *(const s16x4*)vp, hi = *(const s16x4*)(vp + 16);
;         const bf16x8 vf = __builtin_shufflevector(lo, hi, 0, 1, 2, 3, 4, 5, 6, 7);
;         O[d] = MFMA(vf, pf.v, O[d]);
;       }
;     }
;   float rs = rs2.x + rs2.y;
;   rs += __shfl_xor(rs, 32);
;   l += rs;
;     ...
;     if (t + NST - 1 < ntile) {
;       const int sn = (stage == 0) ? NST - 1 : stage - 1;
;       FA_ISSUE(t + NST - 1, sn)
;     }
	v_mfma_f32_32x32x16_bf16 v[50:65], v[232:235], v[66:69], v[50:65]
	s_nop 0
	s_waitcnt lgkmcnt(0)
	v_mfma_f32_32x32x16_bf16 v[34:49], v[236:239], v[66:69], v[34:49]
	v_add_f32_e64 v66, v86, v84
	v_add_f32_e64 v67, v87, v85
	v_add_f32_e64 v66, v88, v66
	v_add_f32_e64 v67, v89, v67
	v_add_f32_e64 v66, v90, v66
	v_add_f32_e64 v67, v91, v67
	v_pk_add_f32 v[84:85], v[92:93], v[66:67]
	v_pk_fma_f32 v[66:67], v[74:75], s[96:97], v[110:111] op_sel_hi:[1,0,0]
	s_nop 0
	v_exp_f32_e32 v66, v66
	v_exp_f32_e32 v67, v67
	v_cndmask_b32_e32 v68, 0, v66, vcc
	v_cmp_lt_f32_e32 vcc, s33, v75
	v_cndmask_b32_e64 v74, v66, v68, s[8:9]
	s_nop 0
	v_cndmask_b32_e32 v69, 0, v67, vcc
	v_cndmask_b32_e64 v75, v67, v69, s[8:9]
	v_pk_fma_f32 v[68:69], v[76:77], s[96:97], v[110:111] op_sel_hi:[1,0,0]
	v_cmp_lt_f32_e32 vcc, s33, v76
	v_exp_f32_e32 v67, v68
	v_exp_f32_e32 v68, v69
	v_cvt_pk_bf16_f32 v66, v74, v75
	v_cndmask_b32_e32 v69, 0, v67, vcc
	v_cmp_lt_f32_e32 vcc, s33, v77
	v_cndmask_b32_e64 v76, v67, v69, s[8:9]
	s_nop 0
	v_cndmask_b32_e32 v70, 0, v68, vcc
	v_cndmask_b32_e64 v77, v68, v70, s[8:9]
	v_pk_fma_f32 v[68:69], v[78:79], s[96:97], v[110:111] op_sel_hi:[1,0,0]
	v_cmp_lt_f32_e32 vcc, s33, v78
	v_exp_f32_e32 v68, v68
	v_exp_f32_e32 v69, v69
	v_cvt_pk_bf16_f32 v67, v76, v77
	v_cndmask_b32_e32 v70, 0, v68, vcc
	v_cmp_lt_f32_e32 vcc, s33, v79
	v_cndmask_b32_e64 v78, v68, v70, s[8:9]
	s_nop 0
	v_cndmask_b32_e32 v71, 0, v69, vcc
	v_cndmask_b32_e64 v79, v69, v71, s[8:9]
	v_pk_fma_f32 v[70:71], v[80:81], s[96:97], v[110:111] op_sel_hi:[1,0,0]
	v_cmp_lt_f32_e32 vcc, s33, v80
	v_exp_f32_e32 v69, v70
	v_exp_f32_e32 v70, v71
	v_cvt_pk_bf16_f32 v68, v78, v79
	v_cndmask_b32_e32 v71, 0, v69, vcc
	v_cmp_lt_f32_e32 vcc, s33, v81
	v_cndmask_b32_e64 v80, v69, v71, s[8:9]
	s_nop 0
	v_cndmask_b32_e32 v72, 0, v70, vcc
	v_cndmask_b32_e64 v81, v70, v72, s[8:9]
	s_nop 0
	v_cvt_pk_bf16_f32 v69, v80, v81
	s_waitcnt lgkmcnt(0)
	s_nop 0
	v_mfma_f32_32x32x16_bf16 v[50:65], v[240:243], v[66:69], v[50:65]
	s_nop 0
	s_waitcnt lgkmcnt(0)
	v_mfma_f32_32x32x16_bf16 v[34:49], v[244:247], v[66:69], v[34:49]
	v_add_f32_e64 v66, v74, v84
	v_add_f32_e64 v67, v75, v85
	v_add_f32_e64 v66, v76, v66
	v_add_f32_e64 v67, v77, v67
	v_add_f32_e64 v66, v78, v66
	v_add_f32_e64 v67, v79, v67
	v_pk_add_f32 v[66:67], v[80:81], v[66:67]
	s_nop 0
	v_add_f32_e32 v66, v66, v67
	ds_bpermute_b32 v67, v165, v66
	s_add_i32 s98, s0, 3
	s_cmp_gt_u32 s98, s46
	s_cbranch_scc1 .Ldma_m_sel1
	s_add_i32 s98, s6, 0xffffb800
	s_cmp_lg_u32 s48, 0
	s_cselect_b32 s98, s98, 0xd800
	s_add_i32 s98, s98, 0
	v_add_u32_e32 v247, s98, v112
	s_nop 0
	v_readfirstlane_b32 s99, v247
	v_add_u32_e32 v247, s98, v111
	s_mov_b32 m0, s99
	v_readfirstlane_b32 s99, v247
	v_add_u32_e32 v247, s98, v113
	global_load_lds_dwordx4 v[108:109], off
	s_mov_b32 m0, s99
	v_readfirstlane_b32 s98, v247
	global_load_lds_dwordx4 v[106:107], off
	s_mov_b32 m0, s98
	s_nop 0
	global_load_lds_dwordx4 v[104:105], off
.Ldma_m_sel1:
	s_waitcnt lgkmcnt(0)
	v_add_f32_e32 v66, v66, v67
	v_add_f32_e32 v164, v164, v66
	s_branch .Ldma_skip_sel1
; #define MFMA(a, b, c) __builtin_amdgcn_mfma_f32_32x32x16_bf16((a), (b), (c), 0, 0, 0)
;     ...
;   const f32x2v c2v = {c2, c2}, mcv = {-mc, -mc};
;   f32x2v rs2 = {0.f, 0.f};
; #pragma unroll
;   for (int ks = 0; ks < 2; ++ks)
; #pragma unroll
;     for (int st = 0; st < 2; ++st) {
;       union { unsigned u[4]; bf16x8 v; } pf;
; #pragma unroll
;       for (int j = 0; j < 4; ++j) {
;         const int i0 = 8 * st + 2 * j;
;         f32x2v t = {S[ks][i0], S[ks][i0 + 1]};
;         t = __builtin_elementwise_fma(t, c2v, mcv);
;         f32x2v pv;
;         if (variant == 1) { pv = t; } else {
;         pv.x = __builtin_amdgcn_exp2f(t.x);
;         pv.y = __builtin_amdgcn_exp2f(t.y);
;         }
;         if (MODE != 0) {
;           if (need_mask) {
;             pv.x = (S[ks][i0] > -1e29f) ? pv.x : 0.f;
;             pv.y = (S[ks][i0 + 1] > -1e29f) ? pv.y : 0.f;
;           }
;         }
;         rs2 += pv;
;         pf.u[j] = __builtin_bit_cast(unsigned, __builtin_convertvector(pv, hwbf16x2));
;       }
; #pragma unroll
;       for (int d = 0; d < DV / 32; ++d) {
;         const char* vp = base + C::KBYTES + (d * 32 + lr) * C::VSTR + (ks * 32 + 16 * st + 4 * lh) * 2;
;         const s16x4 lo = *(const s16x4*)vp, hi = *(const s16x4*)(vp + 16);
;         const bf16x8 vf = __builtin_shufflevector(lo, hi, 0, 1, 2, 3, 4, 5, 6, 7);
;         O[d] = MFMA(vf, pf.v, O[d]);
;       }
;     }
;   float rs = rs2.x + rs2.y;
;   rs += __shfl_xor(rs, 32);
.Lfast_sel1:
	v_mul_f32_e32 v110, 0xbe38aa3b, v110
	v_cndmask_b32_e64 v110, v208, v110, s[10:11]
	v_pk_fma_f32 v[120:121], v[82:83], s[96:97], v[110:111] op_sel_hi:[1,0,0]
	v_exp_f32_e32 v128, v120
	v_exp_f32_e32 v129, v121
	v_pk_fma_f32 v[82:83], v[84:85], s[96:97], v[110:111] op_sel_hi:[1,0,0]
	v_exp_f32_e32 v152, v82
	v_exp_f32_e32 v153, v83
	v_cvt_pk_bf16_f32 v120, v128, v129
	v_pk_fma_f32 v[82:83], v[86:87], s[96:97], v[110:111] op_sel_hi:[1,0,0]
	v_exp_f32_e32 v154, v82
	v_exp_f32_e32 v155, v83
	v_cvt_pk_bf16_f32 v121, v152, v153
	v_pk_fma_f32 v[82:83], v[88:89], s[96:97], v[110:111] op_sel_hi:[1,0,0]
	v_exp_f32_e32 v88, v82
	v_exp_f32_e32 v89, v83
	v_cvt_pk_bf16_f32 v122, v154, v155
	v_cvt_pk_bf16_f32 v123, v88, v89
	s_waitcnt lgkmcnt(0)
	s_nop 0
	v_mfma_f32_32x32x16_bf16 v[50:65], v[216:219], v[120:123], v[50:65]
	s_waitcnt lgkmcnt(0)
	v_mfma_f32_32x32x16_bf16 v[34:49], v[220:223], v[120:123], v[34:49]
	v_add_f32_e64 v84, v128, 0
	v_add_f32_e64 v85, v129, 0
	v_add_f32_e64 v84, v152, v84
	v_add_f32_e64 v85, v153, v85
	v_add_f32_e64 v84, v154, v84
	v_add_f32_e64 v85, v155, v85
	v_pk_add_f32 v[120:121], v[88:89], v[84:85]
	v_pk_fma_f32 v[84:85], v[90:91], s[96:97], v[110:111] op_sel_hi:[1,0,0]
	v_exp_f32_e32 v122, v84
	v_exp_f32_e32 v123, v85
	v_pk_fma_f32 v[86:87], v[92:93], s[96:97], v[110:111] op_sel_hi:[1,0,0]
	v_exp_f32_e32 v92, v86
	v_exp_f32_e32 v93, v87
	v_cvt_pk_bf16_f32 v84, v122, v123
	v_pk_fma_f32 v[86:87], v[94:95], s[96:97], v[110:111] op_sel_hi:[1,0,0]
	v_exp_f32_e32 v94, v86
	v_exp_f32_e32 v95, v87
	v_cvt_pk_bf16_f32 v85, v92, v93
	v_pk_fma_f32 v[88:89], v[96:97], s[96:97], v[110:111] op_sel_hi:[1,0,0]
	v_exp_f32_e32 v96, v88
	v_exp_f32_e32 v97, v89
	v_cvt_pk_bf16_f32 v86, v94, v95
	v_cvt_pk_bf16_f32 v87, v96, v97
	s_nop 1
	v_mfma_f32_32x32x16_bf16 v[50:65], v[224:227], v[84:87], v[50:65]
	s_waitcnt lgkmcnt(0)
	v_mfma_f32_32x32x16_bf16 v[34:49], v[228:231], v[84:87], v[34:49]
	v_fma_f32 v86, v66, s96, v110
	v_fma_f32 v87, v67, s96, v110
	v_fma_f32 v88, v68, s96, v110
	v_fma_f32 v89, v69, s96, v110
	v_exp_f32_e32 v86, v86
	v_exp_f32_e32 v87, v87
	v_pk_add_f32 v[84:85], v[122:123], v[120:121]
	v_pk_add_f32 v[84:85], v[92:93], v[84:85]
	v_exp_f32_e32 v88, v88
	v_exp_f32_e32 v89, v89
	v_cvt_pk_bf16_f32 v66, v86, v87
	v_pk_add_f32 v[84:85], v[94:95], v[84:85]
	v_pk_add_f32 v[84:85], v[96:97], v[84:85]
	v_pk_fma_f32 v[68:69], v[70:71], s[96:97], v[110:111] op_sel_hi:[1,0,0]
	v_exp_f32_e32 v90, v68
	v_exp_f32_e32 v91, v69
	v_cvt_pk_bf16_f32 v67, v88, v89
	v_pk_fma_f32 v[70:71], v[72:73], s[96:97], v[110:111] op_sel_hi:[1,0,0]
	v_exp_f32_e32 v92, v70
	v_exp_f32_e32 v93, v71
	v_cvt_pk_bf16_f32 v68, v90, v91
	v_cvt_pk_bf16_f32 v69, v92, v93
	s_waitcnt lgkmcnt(0)
	s_nop 0
	v_mfma_f32_32x32x16_bf16 v[50:65], v[232:235], v[66:69], v[50:65]
	s_waitcnt lgkmcnt(0)
	v_mfma_f32_32x32x16_bf16 v[34:49], v[236:239], v[66:69], v[34:49]
	v_add_f32_e64 v66, v86, v84
	v_add_f32_e64 v67, v87, v85
	v_add_f32_e64 v66, v88, v66
	v_add_f32_e64 v67, v89, v67
	v_add_f32_e64 v66, v90, v66
	v_add_f32_e64 v67, v91, v67
	v_pk_add_f32 v[84:85], v[92:93], v[66:67]
	v_pk_fma_f32 v[66:67], v[74:75], s[96:97], v[110:111] op_sel_hi:[1,0,0]
	v_exp_f32_e32 v74, v66
	v_exp_f32_e32 v75, v67
	v_pk_fma_f32 v[68:69], v[76:77], s[96:97], v[110:111] op_sel_hi:[1,0,0]
	v_exp_f32_e32 v76, v68
	v_exp_f32_e32 v77, v69
	v_cvt_pk_bf16_f32 v66, v74, v75
	v_pk_fma_f32 v[68:69], v[78:79], s[96:97], v[110:111] op_sel_hi:[1,0,0]
	v_exp_f32_e32 v78, v68
	v_exp_f32_e32 v79, v69
	v_cvt_pk_bf16_f32 v67, v76, v77
	v_pk_fma_f32 v[70:71], v[80:81], s[96:97], v[110:111] op_sel_hi:[1,0,0]
	v_exp_f32_e32 v80, v70
	v_exp_f32_e32 v81, v71
	v_cvt_pk_bf16_f32 v68, v78, v79
	v_cvt_pk_bf16_f32 v69, v80, v81
	s_waitcnt lgkmcnt(0)
	s_nop 0
	v_mfma_f32_32x32x16_bf16 v[50:65], v[240:243], v[66:69], v[50:65]
	s_waitcnt lgkmcnt(0)
	v_mfma_f32_32x32x16_bf16 v[34:49], v[244:247], v[66:69], v[34:49]
	v_add_f32_e64 v66, v74, v84
	v_add_f32_e64 v67, v75, v85
	v_add_f32_e64 v66, v76, v66
	v_add_f32_e64 v67, v77, v67
	v_add_f32_e64 v66, v78, v66
	v_add_f32_e64 v67, v79, v67
	v_pk_add_f32 v[66:67], v[80:81], v[66:67]
	v_add_f32_e32 v66, v66, v67
	ds_bpermute_b32 v67, v165, v66
	s_add_i32 s98, s0, 3
	s_cmp_gt_u32 s98, s46
	s_cbranch_scc1 .Ldma_f_sel1
	s_add_i32 s98, s6, 0xffffb800
	s_cmp_lg_u32 s48, 0
	s_cselect_b32 s98, s98, 0xd800
	s_add_i32 s98, s98, 0
	v_add_u32_e32 v247, s98, v112
	s_nop 0
	v_readfirstlane_b32 s99, v247
	v_add_u32_e32 v247, s98, v111
	s_mov_b32 m0, s99
	v_readfirstlane_b32 s99, v247
	v_add_u32_e32 v247, s98, v113
	global_load_lds_dwordx4 v[108:109], off
	s_mov_b32 m0, s99
	v_readfirstlane_b32 s98, v247
	global_load_lds_dwordx4 v[106:107], off
	s_mov_b32 m0, s98
	s_nop 0
	global_load_lds_dwordx4 v[104:105], off

; #define MFMA(a, b, c) __builtin_amdgcn_mfma_f32_32x32x16_bf16((a), (b), (c), 0, 0, 0)
;     ...
;   float mc = m * c2;
;   if (MODE == 2) mc = selbit ? mc : 1e30f;
;   const f32x2v c2v = {c2, c2}, mcv = {-mc, -mc};
;   f32x2v rs2 = {0.f, 0.f};
; #pragma unroll
;   for (int ks = 0; ks < 2; ++ks)
; #pragma unroll
;     for (int st = 0; st < 2; ++st) {
;       union { unsigned u[4]; bf16x8 v; } pf;
; #pragma unroll
;       for (int j = 0; j < 4; ++j) {
;         const int i0 = 8 * st + 2 * j;
;         f32x2v t = {S[ks][i0], S[ks][i0 + 1]};
;         t = __builtin_elementwise_fma(t, c2v, mcv);
;         f32x2v pv;
;         if (variant == 1) { pv = t; } else {
;         pv.x = __builtin_amdgcn_exp2f(t.x);
;         pv.y = __builtin_amdgcn_exp2f(t.y);
;         }
;         if (MODE != 0) {
;           if (need_mask) {
;             pv.x = (S[ks][i0] > -1e29f) ? pv.x : 0.f;
;             pv.y = (S[ks][i0 + 1] > -1e29f) ? pv.y : 0.f;
;           }
;         }
;         rs2 += pv;
;         pf.u[j] = __builtin_bit_cast(unsigned, __builtin_convertvector(pv, hwbf16x2));
;       }
; #pragma unroll
;       for (int d = 0; d < DV / 32; ++d) {
;         const char* vp = base + C::KBYTES + (d * 32 + lr) * C::VSTR + (ks * 32 + 16 * st + 4 * lh) * 2;
;         const s16x4 lo = *(const s16x4*)vp, hi = *(const s16x4*)(vp + 16);
;         const bf16x8 vf = __builtin_shufflevector(lo, hi, 0, 1, 2, 3, 4, 5, 6, 7);
;         O[d] = MFMA(vf, pf.v, O[d]);
;       }
;     }
.LBB0_455:
	s_cmp_eq_u64 s[8:9], 0
	s_cbranch_scc1 .Lfast_win1
	v_mul_f32_e32 v162, 0xbe38aa3b, v162
	v_pk_fma_f32 v[180:181], v[114:115], s[96:97], v[162:163] op_sel_hi:[1,0,0]
	v_cmp_lt_f32_e32 vcc, s33, v114
	v_exp_f32_e32 v179, v180
	v_exp_f32_e32 v180, v181
	v_cndmask_b32_e32 v114, 0, v179, vcc
	v_cmp_lt_f32_e32 vcc, s33, v115
	v_cndmask_b32_e64 v188, v179, v114, s[8:9]
	s_nop 0
	v_cndmask_b32_e32 v115, 0, v180, vcc
	v_cndmask_b32_e64 v189, v180, v115, s[8:9]
	v_pk_fma_f32 v[114:115], v[116:117], s[96:97], v[162:163] op_sel_hi:[1,0,0]
	v_cmp_lt_f32_e32 vcc, s33, v116
	v_exp_f32_e32 v114, v114
	v_exp_f32_e32 v115, v115
	v_cvt_pk_bf16_f32 v180, v188, v189
	v_cndmask_b32_e32 v116, 0, v114, vcc
	v_cmp_lt_f32_e32 vcc, s33, v117
	v_cndmask_b32_e64 v190, v114, v116, s[8:9]
	s_nop 0
	v_cndmask_b32_e32 v117, 0, v115, vcc
	v_cndmask_b32_e64 v191, v115, v117, s[8:9]
	v_pk_fma_f32 v[114:115], v[118:119], s[96:97], v[162:163] op_sel_hi:[1,0,0]
	v_cmp_lt_f32_e32 vcc, s33, v118
	v_exp_f32_e32 v114, v114
	v_exp_f32_e32 v115, v115
	v_cvt_pk_bf16_f32 v181, v190, v191
	v_cndmask_b32_e32 v116, 0, v114, vcc
	v_cmp_lt_f32_e32 vcc, s33, v119
	v_cndmask_b32_e64 v192, v114, v116, s[8:9]
	s_nop 0
	v_cndmask_b32_e32 v117, 0, v115, vcc
	v_cndmask_b32_e64 v193, v115, v117, s[8:9]
	v_pk_fma_f32 v[114:115], v[120:121], s[96:97], v[162:163] op_sel_hi:[1,0,0]
	v_cmp_lt_f32_e32 vcc, s33, v120
	v_exp_f32_e32 v114, v114
	v_exp_f32_e32 v115, v115
	v_cvt_pk_bf16_f32 v182, v192, v193
	v_cndmask_b32_e32 v116, 0, v114, vcc
	v_cmp_lt_f32_e32 vcc, s33, v121
	v_cndmask_b32_e64 v120, v114, v116, s[8:9]
	s_nop 0
	v_cndmask_b32_e32 v117, 0, v115, vcc
	v_cndmask_b32_e64 v121, v115, v117, s[8:9]
	s_nop 0
	s_nop 0
	s_nop 0
	s_nop 0
	v_cvt_pk_bf16_f32 v183, v120, v121
	s_nop 0
	v_cmp_lt_f32_e32 vcc, s33, v122
	s_waitcnt lgkmcnt(0)
	v_mfma_f32_32x32x16_bf16 v[82:97], v[216:219], v[180:183], v[82:97]
	s_nop 0
	s_waitcnt lgkmcnt(0)
	v_mfma_f32_32x32x16_bf16 v[66:81], v[220:223], v[180:183], v[66:81]
	v_add_f32_e64 v116, v188, 0
	v_add_f32_e64 v117, v189, 0
	v_add_f32_e64 v116, v190, v116
	v_add_f32_e64 v117, v191, v117
	v_add_f32_e64 v116, v192, v116
	v_add_f32_e64 v117, v193, v117
	v_pk_add_f32 v[180:181], v[120:121], v[116:117]
	v_pk_fma_f32 v[116:117], v[122:123], s[96:97], v[162:163] op_sel_hi:[1,0,0]
	s_nop 0
	v_exp_f32_e32 v116, v116
	v_exp_f32_e32 v117, v117
	v_cndmask_b32_e32 v118, 0, v116, vcc
	v_cmp_lt_f32_e32 vcc, s33, v123
	v_cndmask_b32_e64 v182, v116, v118, s[8:9]
	s_nop 0
	v_cndmask_b32_e32 v119, 0, v117, vcc
	v_cndmask_b32_e64 v183, v117, v119, s[8:9]
	v_pk_fma_f32 v[118:119], v[124:125], s[96:97], v[162:163] op_sel_hi:[1,0,0]
	v_cmp_lt_f32_e32 vcc, s33, v124
	v_exp_f32_e32 v117, v118
	v_exp_f32_e32 v118, v119
	v_cvt_pk_bf16_f32 v116, v182, v183
	v_cndmask_b32_e32 v119, 0, v117, vcc
	v_cmp_lt_f32_e32 vcc, s33, v125
	v_cndmask_b32_e64 v124, v117, v119, s[8:9]
	s_nop 0
	v_cndmask_b32_e32 v120, 0, v118, vcc
	v_cndmask_b32_e64 v125, v118, v120, s[8:9]
	v_pk_fma_f32 v[118:119], v[126:127], s[96:97], v[162:163] op_sel_hi:[1,0,0]
	v_cmp_lt_f32_e32 vcc, s33, v126
	v_exp_f32_e32 v118, v118
	v_exp_f32_e32 v119, v119
	v_cvt_pk_bf16_f32 v117, v124, v125
	v_cndmask_b32_e32 v120, 0, v118, vcc
	v_cmp_lt_f32_e32 vcc, s33, v127
	v_cndmask_b32_e64 v126, v118, v120, s[8:9]
	s_nop 0
	v_cndmask_b32_e32 v121, 0, v119, vcc
	v_cndmask_b32_e64 v127, v119, v121, s[8:9]
	v_pk_fma_f32 v[120:121], v[128:129], s[96:97], v[162:163] op_sel_hi:[1,0,0]
	v_cmp_lt_f32_e32 vcc, s33, v128
	v_exp_f32_e32 v119, v120
	v_exp_f32_e32 v120, v121
	v_cvt_pk_bf16_f32 v118, v126, v127
	v_cndmask_b32_e32 v121, 0, v119, vcc
	v_cmp_lt_f32_e32 vcc, s33, v129
	v_cndmask_b32_e64 v128, v119, v121, s[8:9]
	s_nop 0
	v_cndmask_b32_e32 v122, 0, v120, vcc
	v_cndmask_b32_e64 v129, v120, v122, s[8:9]
	s_nop 0
	v_cvt_pk_bf16_f32 v119, v128, v129
	v_cmp_lt_f32_e32 vcc, s33, v98
	s_nop 0
	v_mfma_f32_32x32x16_bf16 v[82:97], v[224:227], v[116:119], v[82:97]
	s_waitcnt lgkmcnt(0)
	v_mfma_f32_32x32x16_bf16 v[66:81], v[228:231], v[116:119], v[66:81]
	v_fma_f32 v118, v98, s96, v162
	v_fma_f32 v119, v99, s96, v162
	v_fma_f32 v120, v100, s96, v162
	v_fma_f32 v121, v101, s96, v162
	v_exp_f32_e32 v118, v118
	v_exp_f32_e32 v119, v119
	v_pk_add_f32 v[116:117], v[182:183], v[180:181]
	v_cndmask_b32_e32 v98, 0, v118, vcc
	v_cmp_lt_f32_e32 vcc, s33, v99
	v_pk_add_f32 v[116:117], v[124:125], v[116:117]
	v_cndmask_b32_e64 v118, v118, v98, s[8:9]
	v_cndmask_b32_e32 v99, 0, v119, vcc
	v_cndmask_b32_e64 v119, v119, v99, s[8:9]
	v_exp_f32_e32 v99, v120
	v_exp_f32_e32 v120, v121
	v_cmp_lt_f32_e32 vcc, s33, v100
	v_cvt_pk_bf16_f32 v98, v118, v119
	v_pk_add_f32 v[116:117], v[126:127], v[116:117]
	v_cndmask_b32_e32 v100, 0, v99, vcc
	v_cmp_lt_f32_e32 vcc, s33, v101
	v_pk_add_f32 v[116:117], v[128:129], v[116:117]
	s_nop 0
	v_cndmask_b32_e32 v101, 0, v120, vcc
	v_cndmask_b32_e64 v121, v120, v101, s[8:9]
	v_cndmask_b32_e64 v120, v99, v100, s[8:9]
	v_pk_fma_f32 v[100:101], v[102:103], s[96:97], v[162:163] op_sel_hi:[1,0,0]
	v_cmp_lt_f32_e32 vcc, s33, v102
	v_exp_f32_e32 v100, v100
	v_exp_f32_e32 v101, v101
	v_cvt_pk_bf16_f32 v99, v120, v121
	v_cndmask_b32_e32 v102, 0, v100, vcc
	v_cmp_lt_f32_e32 vcc, s33, v103
	v_cndmask_b32_e64 v122, v100, v102, s[8:9]
	s_nop 0
	v_cndmask_b32_e32 v103, 0, v101, vcc
	v_cndmask_b32_e64 v123, v101, v103, s[8:9]
	v_pk_fma_f32 v[102:103], v[104:105], s[96:97], v[162:163] op_sel_hi:[1,0,0]
	v_cmp_lt_f32_e32 vcc, s33, v104
	v_exp_f32_e32 v101, v102
	v_exp_f32_e32 v102, v103
	v_cvt_pk_bf16_f32 v100, v122, v123
	v_cndmask_b32_e32 v103, 0, v101, vcc
	v_cmp_lt_f32_e32 vcc, s33, v105
	v_cndmask_b32_e64 v124, v101, v103, s[8:9]
	s_nop 0
	v_cndmask_b32_e32 v104, 0, v102, vcc
	v_cndmask_b32_e64 v125, v102, v104, s[8:9]
	s_nop 0
	v_cvt_pk_bf16_f32 v101, v124, v125
	v_cmp_lt_f32_e32 vcc, s33, v106
	s_waitcnt lgkmcnt(0)
; #define MFMA(a, b, c) __builtin_amdgcn_mfma_f32_32x32x16_bf16((a), (b), (c), 0, 0, 0)
;     ...
; #pragma unroll
;       for (int d = 0; d < DV / 32; ++d) {
;         const char* vp = base + C::KBYTES + (d * 32 + lr) * C::VSTR + (ks * 32 + 16 * st + 4 * lh) * 2;
;         const s16x4 lo = *(const s16x4*)vp, hi = *(const s16x4*)(vp + 16);
;         const bf16x8 vf = __builtin_shufflevector(lo, hi, 0, 1, 2, 3, 4, 5, 6, 7);
;         O[d] = MFMA(vf, pf.v, O[d]);
;       }
;     }
;   float rs = rs2.x + rs2.y;
;   rs += __shfl_xor(rs, 32);
;   l += rs;
;     ...
;     if (t + NST - 1 < ntile) {
;       const int sn = (stage == 0) ? NST - 1 : stage - 1;
;       FA_ISSUE(t + NST - 1, sn)
;     }
	v_mfma_f32_32x32x16_bf16 v[82:97], v[232:235], v[98:101], v[82:97]
	s_nop 0
	s_waitcnt lgkmcnt(0)
	v_mfma_f32_32x32x16_bf16 v[66:81], v[236:239], v[98:101], v[66:81]
	v_add_f32_e64 v98, v118, v116
	v_add_f32_e64 v99, v119, v117
	v_add_f32_e64 v98, v120, v98
	v_add_f32_e64 v99, v121, v99
	v_add_f32_e64 v98, v122, v98
	v_add_f32_e64 v99, v123, v99
	v_pk_add_f32 v[116:117], v[124:125], v[98:99]
	v_pk_fma_f32 v[98:99], v[106:107], s[96:97], v[162:163] op_sel_hi:[1,0,0]
	s_nop 0
	v_exp_f32_e32 v98, v98
	v_exp_f32_e32 v99, v99
	v_cndmask_b32_e32 v100, 0, v98, vcc
	v_cmp_lt_f32_e32 vcc, s33, v107
	v_cndmask_b32_e64 v106, v98, v100, s[8:9]
	s_nop 0
	v_cndmask_b32_e32 v101, 0, v99, vcc
	v_cndmask_b32_e64 v107, v99, v101, s[8:9]
	v_pk_fma_f32 v[100:101], v[108:109], s[96:97], v[162:163] op_sel_hi:[1,0,0]
	v_cmp_lt_f32_e32 vcc, s33, v108
	v_exp_f32_e32 v99, v100
	v_exp_f32_e32 v100, v101
	v_cvt_pk_bf16_f32 v98, v106, v107
	v_cndmask_b32_e32 v101, 0, v99, vcc
	v_cmp_lt_f32_e32 vcc, s33, v109
	v_cndmask_b32_e64 v108, v99, v101, s[8:9]
	s_nop 0
	v_cndmask_b32_e32 v102, 0, v100, vcc
	v_cndmask_b32_e64 v109, v100, v102, s[8:9]
	v_pk_fma_f32 v[100:101], v[110:111], s[96:97], v[162:163] op_sel_hi:[1,0,0]
	v_cmp_lt_f32_e32 vcc, s33, v110
	v_exp_f32_e32 v100, v100
	v_exp_f32_e32 v101, v101
	v_cvt_pk_bf16_f32 v99, v108, v109
	v_cndmask_b32_e32 v102, 0, v100, vcc
	v_cmp_lt_f32_e32 vcc, s33, v111
	v_cndmask_b32_e64 v110, v100, v102, s[8:9]
	s_nop 0
	v_cndmask_b32_e32 v103, 0, v101, vcc
	v_cndmask_b32_e64 v111, v101, v103, s[8:9]
	v_pk_fma_f32 v[102:103], v[112:113], s[96:97], v[162:163] op_sel_hi:[1,0,0]
	v_cmp_lt_f32_e32 vcc, s33, v112
	v_exp_f32_e32 v101, v102
	v_exp_f32_e32 v102, v103
	v_cvt_pk_bf16_f32 v100, v110, v111
	v_cndmask_b32_e32 v103, 0, v101, vcc
	v_cmp_lt_f32_e32 vcc, s33, v113
	v_cndmask_b32_e64 v112, v101, v103, s[8:9]
	s_nop 0
	v_cndmask_b32_e32 v104, 0, v102, vcc
	v_cndmask_b32_e64 v113, v102, v104, s[8:9]
	s_nop 0
	v_cvt_pk_bf16_f32 v101, v112, v113
	s_waitcnt lgkmcnt(0)
	s_nop 0
	v_mfma_f32_32x32x16_bf16 v[82:97], v[240:243], v[98:101], v[82:97]
	s_nop 0
	s_waitcnt lgkmcnt(0)
	v_mfma_f32_32x32x16_bf16 v[66:81], v[244:247], v[98:101], v[66:81]
	v_add_f32_e64 v98, v106, v116
	v_add_f32_e64 v99, v107, v117
	v_add_f32_e64 v98, v108, v98
	v_add_f32_e64 v99, v109, v99
	v_add_f32_e64 v98, v110, v98
	v_add_f32_e64 v99, v111, v99
	v_pk_add_f32 v[98:99], v[112:113], v[98:99]
	s_nop 0
	v_add_f32_e32 v98, v98, v99
	ds_bpermute_b32 v99, v165, v98
	s_cmp_gt_u32 s19, 5
	s_cbranch_scc1 .Ldma_m_win1
	s_add_i32 s98, s0, 0xffffb800
	s_cmp_lg_u32 s21, 0
	s_cselect_b32 s98, s98, 0xd800
	s_add_i32 s98, s98, 0
	v_add_u32_e32 v247, s98, v170
	s_nop 0
	v_readfirstlane_b32 s99, v247
	v_add_u32_e32 v247, s98, v169
	s_mov_b32 m0, s99
	v_readfirstlane_b32 s99, v247
	v_add_u32_e32 v247, s98, v171
	global_load_lds_dwordx4 v[160:161], off
	s_mov_b32 m0, s99
	v_readfirstlane_b32 s98, v247
	global_load_lds_dwordx4 v[158:159], off
	s_mov_b32 m0, s98
	s_nop 0
	global_load_lds_dwordx4 v[156:157], off
.Ldma_m_win1:
	s_waitcnt lgkmcnt(0)
	v_add_f32_e32 v98, v98, v99
	v_add_f32_e32 v172, v172, v98
	s_branch .Ldma_skip_win1
; #define MFMA(a, b, c) __builtin_amdgcn_mfma_f32_32x32x16_bf16((a), (b), (c), 0, 0, 0)
;     ...
;   const f32x2v c2v = {c2, c2}, mcv = {-mc, -mc};
;   f32x2v rs2 = {0.f, 0.f};
; #pragma unroll
;   for (int ks = 0; ks < 2; ++ks)
; #pragma unroll
;     for (int st = 0; st < 2; ++st) {
;       union { unsigned u[4]; bf16x8 v; } pf;
; #pragma unroll
;       for (int j = 0; j < 4; ++j) {
;         const int i0 = 8 * st + 2 * j;
;         f32x2v t = {S[ks][i0], S[ks][i0 + 1]};
;         t = __builtin_elementwise_fma(t, c2v, mcv);
;         f32x2v pv;
;         if (variant == 1) { pv = t; } else {
;         pv.x = __builtin_amdgcn_exp2f(t.x);
;         pv.y = __builtin_amdgcn_exp2f(t.y);
;         }
;         if (MODE != 0) {
;           if (need_mask) {
;             pv.x = (S[ks][i0] > -1e29f) ? pv.x : 0.f;
;             pv.y = (S[ks][i0 + 1] > -1e29f) ? pv.y : 0.f;
;           }
;         }
;         rs2 += pv;
;         pf.u[j] = __builtin_bit_cast(unsigned, __builtin_convertvector(pv, hwbf16x2));
;       }
; #pragma unroll
;       for (int d = 0; d < DV / 32; ++d) {
;         const char* vp = base + C::KBYTES + (d * 32 + lr) * C::VSTR + (ks * 32 + 16 * st + 4 * lh) * 2;
;         const s16x4 lo = *(const s16x4*)vp, hi = *(const s16x4*)(vp + 16);
;         const bf16x8 vf = __builtin_shufflevector(lo, hi, 0, 1, 2, 3, 4, 5, 6, 7);
;         O[d] = MFMA(vf, pf.v, O[d]);
;       }
;     }
;   float rs = rs2.x + rs2.y;
;   rs += __shfl_xor(rs, 32);
.Lfast_win1:
	v_mul_f32_e32 v162, 0xbe38aa3b, v162
	v_pk_fma_f32 v[180:181], v[114:115], s[96:97], v[162:163] op_sel_hi:[1,0,0]
	v_exp_f32_e32 v188, v180
	v_exp_f32_e32 v189, v181
	v_pk_fma_f32 v[114:115], v[116:117], s[96:97], v[162:163] op_sel_hi:[1,0,0]
	v_exp_f32_e32 v190, v114
	v_exp_f32_e32 v191, v115
	v_cvt_pk_bf16_f32 v180, v188, v189
	v_pk_fma_f32 v[114:115], v[118:119], s[96:97], v[162:163] op_sel_hi:[1,0,0]
	v_exp_f32_e32 v192, v114
	v_exp_f32_e32 v193, v115
	v_cvt_pk_bf16_f32 v181, v190, v191
	v_pk_fma_f32 v[114:115], v[120:121], s[96:97], v[162:163] op_sel_hi:[1,0,0]
	v_exp_f32_e32 v120, v114
	v_exp_f32_e32 v121, v115
	v_cvt_pk_bf16_f32 v182, v192, v193
	v_cvt_pk_bf16_f32 v183, v120, v121
	s_waitcnt lgkmcnt(0)
	s_nop 0
	v_mfma_f32_32x32x16_bf16 v[82:97], v[216:219], v[180:183], v[82:97]
	s_waitcnt lgkmcnt(0)
	v_mfma_f32_32x32x16_bf16 v[66:81], v[220:223], v[180:183], v[66:81]
	v_add_f32_e64 v116, v188, 0
	v_add_f32_e64 v117, v189, 0
	v_add_f32_e64 v116, v190, v116
	v_add_f32_e64 v117, v191, v117
	v_add_f32_e64 v116, v192, v116
	v_add_f32_e64 v117, v193, v117
	v_pk_add_f32 v[180:181], v[120:121], v[116:117]
	v_pk_fma_f32 v[116:117], v[122:123], s[96:97], v[162:163] op_sel_hi:[1,0,0]
	v_exp_f32_e32 v182, v116
	v_exp_f32_e32 v183, v117
	v_pk_fma_f32 v[118:119], v[124:125], s[96:97], v[162:163] op_sel_hi:[1,0,0]
	v_exp_f32_e32 v124, v118
	v_exp_f32_e32 v125, v119
	v_cvt_pk_bf16_f32 v116, v182, v183
	v_pk_fma_f32 v[118:119], v[126:127], s[96:97], v[162:163] op_sel_hi:[1,0,0]
	v_exp_f32_e32 v126, v118
	v_exp_f32_e32 v127, v119
	v_cvt_pk_bf16_f32 v117, v124, v125
	v_pk_fma_f32 v[120:121], v[128:129], s[96:97], v[162:163] op_sel_hi:[1,0,0]
	v_exp_f32_e32 v128, v120
	v_exp_f32_e32 v129, v121
	v_cvt_pk_bf16_f32 v118, v126, v127
	v_cvt_pk_bf16_f32 v119, v128, v129
	s_nop 1
	v_mfma_f32_32x32x16_bf16 v[82:97], v[224:227], v[116:119], v[82:97]
	s_waitcnt lgkmcnt(0)
	v_mfma_f32_32x32x16_bf16 v[66:81], v[228:231], v[116:119], v[66:81]
	v_fma_f32 v118, v98, s96, v162
	v_fma_f32 v119, v99, s96, v162
	v_fma_f32 v120, v100, s96, v162
	v_fma_f32 v121, v101, s96, v162
	v_exp_f32_e32 v118, v118
	v_exp_f32_e32 v119, v119
	v_pk_add_f32 v[116:117], v[182:183], v[180:181]
	v_pk_add_f32 v[116:117], v[124:125], v[116:117]
	v_exp_f32_e32 v120, v120
	v_exp_f32_e32 v121, v121
	v_cvt_pk_bf16_f32 v98, v118, v119
	v_pk_add_f32 v[116:117], v[126:127], v[116:117]
	v_pk_add_f32 v[116:117], v[128:129], v[116:117]
	v_pk_fma_f32 v[100:101], v[102:103], s[96:97], v[162:163] op_sel_hi:[1,0,0]
	v_exp_f32_e32 v122, v100
	v_exp_f32_e32 v123, v101
	v_cvt_pk_bf16_f32 v99, v120, v121
	v_pk_fma_f32 v[102:103], v[104:105], s[96:97], v[162:163] op_sel_hi:[1,0,0]
	v_exp_f32_e32 v124, v102
	v_exp_f32_e32 v125, v103
	v_cvt_pk_bf16_f32 v100, v122, v123
	v_cvt_pk_bf16_f32 v101, v124, v125
	s_waitcnt lgkmcnt(0)
	s_nop 0
	v_mfma_f32_32x32x16_bf16 v[82:97], v[232:235], v[98:101], v[82:97]
	s_waitcnt lgkmcnt(0)
	v_mfma_f32_32x32x16_bf16 v[66:81], v[236:239], v[98:101], v[66:81]
	v_add_f32_e64 v98, v118, v116
	v_add_f32_e64 v99, v119, v117
	v_add_f32_e64 v98, v120, v98
	v_add_f32_e64 v99, v121, v99
	v_add_f32_e64 v98, v122, v98
	v_add_f32_e64 v99, v123, v99
	v_pk_add_f32 v[116:117], v[124:125], v[98:99]
	v_pk_fma_f32 v[98:99], v[106:107], s[96:97], v[162:163] op_sel_hi:[1,0,0]
	v_exp_f32_e32 v106, v98
	v_exp_f32_e32 v107, v99
	v_pk_fma_f32 v[100:101], v[108:109], s[96:97], v[162:163] op_sel_hi:[1,0,0]
	v_exp_f32_e32 v108, v100
	v_exp_f32_e32 v109, v101
	v_cvt_pk_bf16_f32 v98, v106, v107
	v_pk_fma_f32 v[100:101], v[110:111], s[96:97], v[162:163] op_sel_hi:[1,0,0]
	v_exp_f32_e32 v110, v100
	v_exp_f32_e32 v111, v101
	v_cvt_pk_bf16_f32 v99, v108, v109
	v_pk_fma_f32 v[102:103], v[112:113], s[96:97], v[162:163] op_sel_hi:[1,0,0]
	v_exp_f32_e32 v112, v102
	v_exp_f32_e32 v113, v103
	v_cvt_pk_bf16_f32 v100, v110, v111
	v_cvt_pk_bf16_f32 v101, v112, v113
	s_waitcnt lgkmcnt(0)
	s_nop 0
	v_mfma_f32_32x32x16_bf16 v[82:97], v[240:243], v[98:101], v[82:97]
	s_waitcnt lgkmcnt(0)
	v_mfma_f32_32x32x16_bf16 v[66:81], v[244:247], v[98:101], v[66:81]
	v_add_f32_e64 v98, v106, v116
	v_add_f32_e64 v99, v107, v117
	v_add_f32_e64 v98, v108, v98
	v_add_f32_e64 v99, v109, v99
	v_add_f32_e64 v98, v110, v98
	v_add_f32_e64 v99, v111, v99
	v_pk_add_f32 v[98:99], v[112:113], v[98:99]
	v_add_f32_e32 v98, v98, v99
	ds_bpermute_b32 v99, v165, v98
	s_cmp_gt_u32 s19, 5
	s_cbranch_scc1 .Ldma_f_win1
	s_add_i32 s98, s0, 0xffffb800
	s_cmp_lg_u32 s21, 0
	s_cselect_b32 s98, s98, 0xd800
	s_add_i32 s98, s98, 0
	v_add_u32_e32 v247, s98, v170
	s_nop 0
	v_readfirstlane_b32 s99, v247
	v_add_u32_e32 v247, s98, v169
	s_mov_b32 m0, s99
	v_readfirstlane_b32 s99, v247
	v_add_u32_e32 v247, s98, v171
	global_load_lds_dwordx4 v[160:161], off
	s_mov_b32 m0, s99
	v_readfirstlane_b32 s98, v247
	global_load_lds_dwordx4 v[158:159], off
	s_mov_b32 m0, s98
	s_nop 0
	global_load_lds_dwordx4 v[156:157], off

; #define MFMA(a, b, c) __builtin_amdgcn_mfma_f32_32x32x16_bf16((a), (b), (c), 0, 0, 0)
;     ...
;   float mc = m * c2;
;   if (MODE == 2) mc = selbit ? mc : 1e30f;
;   const f32x2v c2v = {c2, c2}, mcv = {-mc, -mc};
;   f32x2v rs2 = {0.f, 0.f};
; #pragma unroll
;   for (int ks = 0; ks < 2; ++ks)
; #pragma unroll
;     for (int st = 0; st < 2; ++st) {
;       union { unsigned u[4]; bf16x8 v; } pf;
; #pragma unroll
;       for (int j = 0; j < 4; ++j) {
;         const int i0 = 8 * st + 2 * j;
;         f32x2v t = {S[ks][i0], S[ks][i0 + 1]};
;         t = __builtin_elementwise_fma(t, c2v, mcv);
;         f32x2v pv;
;         if (variant == 1) { pv = t; } else {
;         pv.x = __builtin_amdgcn_exp2f(t.x);
;         pv.y = __builtin_amdgcn_exp2f(t.y);
;         }
;         if (MODE != 0) {
;           if (need_mask) {
;             pv.x = (S[ks][i0] > -1e29f) ? pv.x : 0.f;
;             pv.y = (S[ks][i0 + 1] > -1e29f) ? pv.y : 0.f;
;           }
;         }
;         rs2 += pv;
;         pf.u[j] = __builtin_bit_cast(unsigned, __builtin_convertvector(pv, hwbf16x2));
;       }
; #pragma unroll
;       for (int d = 0; d < DV / 32; ++d) {
;         const char* vp = base + C::KBYTES + (d * 32 + lr) * C::VSTR + (ks * 32 + 16 * st + 4 * lh) * 2;
;         const s16x4 lo = *(const s16x4*)vp, hi = *(const s16x4*)(vp + 16);
;         const bf16x8 vf = __builtin_shufflevector(lo, hi, 0, 1, 2, 3, 4, 5, 6, 7);
;         O[d] = MFMA(vf, pf.v, O[d]);
.LBB0_487:
	s_cmp_eq_u64 s[8:9], 0
	s_cbranch_scc1 .Lfast_mla2
	v_mul_f32_e32 v104, 0xbe16c740, v104
	s_mov_b32 s12, 0x3e16c740
	v_pk_fma_f32 v[118:119], v[50:51], s[12:13], v[104:105] op_sel_hi:[1,0,0]
	v_cmp_lt_f32_e32 vcc, s33, v50
	v_exp_f32_e32 v117, v118
	v_exp_f32_e32 v118, v119
	v_cndmask_b32_e32 v50, 0, v117, vcc
	v_cmp_lt_f32_e32 vcc, s33, v51
	v_cndmask_b32_e64 v126, v117, v50, s[8:9]
	s_nop 0
	v_cndmask_b32_e32 v51, 0, v118, vcc
	v_cndmask_b32_e64 v127, v118, v51, s[8:9]
	v_pk_fma_f32 v[50:51], v[52:53], s[12:13], v[104:105] op_sel_hi:[1,0,0]
	v_cmp_lt_f32_e32 vcc, s33, v52
	v_exp_f32_e32 v50, v50
	v_exp_f32_e32 v51, v51
	v_cvt_pk_bf16_f32 v118, v126, v127
	v_cndmask_b32_e32 v52, 0, v50, vcc
	v_cmp_lt_f32_e32 vcc, s33, v53
	v_cndmask_b32_e64 v128, v50, v52, s[8:9]
	s_nop 0
	v_cndmask_b32_e32 v53, 0, v51, vcc
	v_cndmask_b32_e64 v129, v51, v53, s[8:9]
	v_pk_fma_f32 v[50:51], v[54:55], s[12:13], v[104:105] op_sel_hi:[1,0,0]
	v_cmp_lt_f32_e32 vcc, s33, v54
	v_exp_f32_e32 v50, v50
	v_exp_f32_e32 v51, v51
	v_cvt_pk_bf16_f32 v119, v128, v129
	v_cndmask_b32_e32 v52, 0, v50, vcc
	v_cmp_lt_f32_e32 vcc, s33, v55
	v_cndmask_b32_e64 v130, v50, v52, s[8:9]
	s_nop 0
	v_cndmask_b32_e32 v53, 0, v51, vcc
	v_cndmask_b32_e64 v131, v51, v53, s[8:9]
	v_pk_fma_f32 v[50:51], v[56:57], s[12:13], v[104:105] op_sel_hi:[1,0,0]
	v_cmp_lt_f32_e32 vcc, s33, v56
	v_exp_f32_e32 v50, v50
	v_exp_f32_e32 v51, v51
	v_cvt_pk_bf16_f32 v120, v130, v131
	v_cndmask_b32_e32 v52, 0, v50, vcc
	v_cmp_lt_f32_e32 vcc, s33, v57
	v_cndmask_b32_e64 v56, v50, v52, s[8:9]
	s_nop 0
	v_cndmask_b32_e32 v53, 0, v51, vcc
	v_cndmask_b32_e64 v57, v51, v53, s[8:9]
	v_cvt_pk_bf16_f32 v121, v56, v57
	v_cmp_lt_f32_e32 vcc, s33, v58
	s_waitcnt lgkmcnt(0)
	v_mfma_f32_32x32x16_bf16 v[18:33], v[216:219], v[118:121], v[18:33]
	s_waitcnt lgkmcnt(0)
	v_mfma_f32_32x32x16_bf16 v[2:17], v[220:223], v[118:121], v[2:17]
	v_add_f32_e64 v52, v126, 0
	v_add_f32_e64 v53, v127, 0
	v_add_f32_e64 v52, v128, v52
	v_add_f32_e64 v53, v129, v53
	v_add_f32_e64 v52, v130, v52
	v_add_f32_e64 v53, v131, v53
	v_pk_add_f32 v[118:119], v[56:57], v[52:53]
	v_pk_fma_f32 v[52:53], v[58:59], s[12:13], v[104:105] op_sel_hi:[1,0,0]
	s_nop 0
	v_exp_f32_e32 v52, v52
	v_exp_f32_e32 v53, v53
	v_cndmask_b32_e32 v54, 0, v52, vcc
	v_cmp_lt_f32_e32 vcc, s33, v59
	v_cndmask_b32_e64 v120, v52, v54, s[8:9]
	s_nop 0
	v_cndmask_b32_e32 v55, 0, v53, vcc
	v_cndmask_b32_e64 v121, v53, v55, s[8:9]
	v_pk_fma_f32 v[54:55], v[60:61], s[12:13], v[104:105] op_sel_hi:[1,0,0]
	v_cmp_lt_f32_e32 vcc, s33, v60
	v_exp_f32_e32 v53, v54
	v_exp_f32_e32 v54, v55
	v_cvt_pk_bf16_f32 v52, v120, v121
	v_cndmask_b32_e32 v55, 0, v53, vcc
	v_cmp_lt_f32_e32 vcc, s33, v61
	v_cndmask_b32_e64 v60, v53, v55, s[8:9]
	s_nop 0
	v_cndmask_b32_e32 v56, 0, v54, vcc
	v_cndmask_b32_e64 v61, v54, v56, s[8:9]
	v_pk_fma_f32 v[54:55], v[62:63], s[12:13], v[104:105] op_sel_hi:[1,0,0]
	v_cmp_lt_f32_e32 vcc, s33, v62
	v_exp_f32_e32 v54, v54
	v_exp_f32_e32 v55, v55
	v_cvt_pk_bf16_f32 v53, v60, v61
	v_cndmask_b32_e32 v56, 0, v54, vcc
	v_cmp_lt_f32_e32 vcc, s33, v63
	v_cndmask_b32_e64 v62, v54, v56, s[8:9]
	s_nop 0
	v_cndmask_b32_e32 v57, 0, v55, vcc
	v_cndmask_b32_e64 v63, v55, v57, s[8:9]
	v_pk_fma_f32 v[56:57], v[64:65], s[12:13], v[104:105] op_sel_hi:[1,0,0]
	v_cmp_lt_f32_e32 vcc, s33, v64
	v_exp_f32_e32 v55, v56
	v_exp_f32_e32 v56, v57
	v_cvt_pk_bf16_f32 v54, v62, v63
	v_cndmask_b32_e32 v57, 0, v55, vcc
	v_cmp_lt_f32_e32 vcc, s33, v65
	v_cndmask_b32_e64 v64, v55, v57, s[8:9]
	s_nop 0
	v_cndmask_b32_e32 v58, 0, v56, vcc
	v_cndmask_b32_e64 v65, v56, v58, s[8:9]
	v_cvt_pk_bf16_f32 v55, v64, v65
	v_cmp_lt_f32_e32 vcc, s33, v34
	s_nop 0
	v_mfma_f32_32x32x16_bf16 v[18:33], v[224:227], v[52:55], v[18:33]
	s_waitcnt lgkmcnt(0)
; #define MFMA(a, b, c) __builtin_amdgcn_mfma_f32_32x32x16_bf16((a), (b), (c), 0, 0, 0)
; template <int N> DI void wait_vmcnt() { asm volatile("s_waitcnt vmcnt(%0)" ::"n"(N) : "memory"); }
;     ...
; #pragma unroll
;       for (int j = 0; j < 4; ++j) {
;         const int i0 = 8 * st + 2 * j;
;         f32x2v t = {S[ks][i0], S[ks][i0 + 1]};
;         t = __builtin_elementwise_fma(t, c2v, mcv);
;         f32x2v pv;
;         if (variant == 1) { pv = t; } else {
;         pv.x = __builtin_amdgcn_exp2f(t.x);
;         pv.y = __builtin_amdgcn_exp2f(t.y);
;         }
;         if (MODE != 0) {
;           if (need_mask) {
;             pv.x = (S[ks][i0] > -1e29f) ? pv.x : 0.f;
;             pv.y = (S[ks][i0 + 1] > -1e29f) ? pv.y : 0.f;
;           }
;         }
;         rs2 += pv;
;         pf.u[j] = __builtin_bit_cast(unsigned, __builtin_convertvector(pv, hwbf16x2));
;       }
; #pragma unroll
;       for (int d = 0; d < DV / 32; ++d) {
;         const char* vp = base + C::KBYTES + (d * 32 + lr) * C::VSTR + (ks * 32 + 16 * st + 4 * lh) * 2;
;         const s16x4 lo = *(const s16x4*)vp, hi = *(const s16x4*)(vp + 16);
;         const bf16x8 vf = __builtin_shufflevector(lo, hi, 0, 1, 2, 3, 4, 5, 6, 7);
;         O[d] = MFMA(vf, pf.v, O[d]);
;       }
;     }
;   float rs = rs2.x + rs2.y;
;   rs += __shfl_xor(rs, 32);
;     ...
;   asm volatile("s_waitcnt vmcnt(0)" ::: "memory");
; #pragma unroll
;   for (int t = 0; t < NST - 1; ++t)
;     if (t < ntile) FA_ISSUE(t, t)
;   int stage = 0;
;   for (int t = 0; t < ntile; ++t) {
;     int ahead = ((ntile < t + NST - 1) ? ntile : t + NST - 1) - (t + 1);
;     if (NST == 4 && ahead >= 2) wait_vmcnt<2 * NI>();
;     else if (ahead >= 1) wait_vmcnt<NI>();
;     else wait_vmcnt<0>();
;     raw_barrier();
;     if (t + NST - 1 < ntile) {
;       const int sn = (stage == 0) ? NST - 1 : stage - 1;
;       FA_ISSUE(t + NST - 1, sn)
	v_mfma_f32_32x32x16_bf16 v[2:17], v[228:231], v[52:55], v[2:17]
	v_fma_f32 v54, v34, s12, v104
	v_fma_f32 v55, v35, s12, v104
	v_fma_f32 v56, v36, s12, v104
	v_fma_f32 v57, v37, s12, v104
	v_exp_f32_e32 v54, v54
	v_exp_f32_e32 v55, v55
	v_pk_add_f32 v[52:53], v[120:121], v[118:119]
	v_cndmask_b32_e32 v34, 0, v54, vcc
	v_cmp_lt_f32_e32 vcc, s33, v35
	v_pk_add_f32 v[52:53], v[60:61], v[52:53]
	v_cndmask_b32_e64 v54, v54, v34, s[8:9]
	v_cndmask_b32_e32 v35, 0, v55, vcc
	v_cndmask_b32_e64 v55, v55, v35, s[8:9]
	v_exp_f32_e32 v35, v56
	v_exp_f32_e32 v56, v57
	v_cmp_lt_f32_e32 vcc, s33, v36
	v_cvt_pk_bf16_f32 v34, v54, v55
	v_pk_add_f32 v[52:53], v[62:63], v[52:53]
	v_cndmask_b32_e32 v36, 0, v35, vcc
	v_cmp_lt_f32_e32 vcc, s33, v37
	v_pk_add_f32 v[52:53], v[64:65], v[52:53]
	s_nop 0
	v_cndmask_b32_e32 v37, 0, v56, vcc
	v_cndmask_b32_e64 v57, v56, v37, s[8:9]
	v_cndmask_b32_e64 v56, v35, v36, s[8:9]
	v_pk_fma_f32 v[36:37], v[38:39], s[12:13], v[104:105] op_sel_hi:[1,0,0]
	v_cmp_lt_f32_e32 vcc, s33, v38
	v_exp_f32_e32 v36, v36
	v_exp_f32_e32 v37, v37
	v_cvt_pk_bf16_f32 v35, v56, v57
	v_cndmask_b32_e32 v38, 0, v36, vcc
	v_cmp_lt_f32_e32 vcc, s33, v39
	v_cndmask_b32_e64 v58, v36, v38, s[8:9]
	s_nop 0
	v_cndmask_b32_e32 v39, 0, v37, vcc
	v_cndmask_b32_e64 v59, v37, v39, s[8:9]
	v_pk_fma_f32 v[38:39], v[40:41], s[12:13], v[104:105] op_sel_hi:[1,0,0]
	v_cmp_lt_f32_e32 vcc, s33, v40
	v_exp_f32_e32 v37, v38
	v_exp_f32_e32 v38, v39
	v_cvt_pk_bf16_f32 v36, v58, v59
	v_cndmask_b32_e32 v39, 0, v37, vcc
	v_cmp_lt_f32_e32 vcc, s33, v41
	v_cndmask_b32_e64 v60, v37, v39, s[8:9]
	s_nop 0
	v_cndmask_b32_e32 v40, 0, v38, vcc
	v_cndmask_b32_e64 v61, v38, v40, s[8:9]
	v_cvt_pk_bf16_f32 v37, v60, v61
	v_cmp_lt_f32_e32 vcc, s33, v42
	s_waitcnt lgkmcnt(0)
	v_mfma_f32_32x32x16_bf16 v[18:33], v[232:235], v[34:37], v[18:33]
	s_waitcnt lgkmcnt(0)
	v_mfma_f32_32x32x16_bf16 v[2:17], v[236:239], v[34:37], v[2:17]
	v_add_f32_e64 v34, v54, v52
	v_add_f32_e64 v35, v55, v53
	v_add_f32_e64 v34, v56, v34
	v_add_f32_e64 v35, v57, v35
	v_add_f32_e64 v34, v58, v34
	v_add_f32_e64 v35, v59, v35
	v_pk_add_f32 v[52:53], v[60:61], v[34:35]
	v_pk_fma_f32 v[34:35], v[42:43], s[12:13], v[104:105] op_sel_hi:[1,0,0]
	s_nop 0
	v_exp_f32_e32 v34, v34
	v_exp_f32_e32 v35, v35
	v_cndmask_b32_e32 v36, 0, v34, vcc
	v_cmp_lt_f32_e32 vcc, s33, v43
	v_cndmask_b32_e64 v42, v34, v36, s[8:9]
	s_nop 0
	v_cndmask_b32_e32 v37, 0, v35, vcc
	v_cndmask_b32_e64 v43, v35, v37, s[8:9]
	v_pk_fma_f32 v[36:37], v[44:45], s[12:13], v[104:105] op_sel_hi:[1,0,0]
	v_cmp_lt_f32_e32 vcc, s33, v44
	v_exp_f32_e32 v35, v36
	v_exp_f32_e32 v36, v37
	v_cvt_pk_bf16_f32 v34, v42, v43
	v_cndmask_b32_e32 v37, 0, v35, vcc
	v_cmp_lt_f32_e32 vcc, s33, v45
	v_cndmask_b32_e64 v44, v35, v37, s[8:9]
	s_nop 0
	v_cndmask_b32_e32 v38, 0, v36, vcc
	v_cndmask_b32_e64 v45, v36, v38, s[8:9]
	v_pk_fma_f32 v[36:37], v[46:47], s[12:13], v[104:105] op_sel_hi:[1,0,0]
	v_cmp_lt_f32_e32 vcc, s33, v46
	v_exp_f32_e32 v36, v36
	v_exp_f32_e32 v37, v37
	v_cvt_pk_bf16_f32 v35, v44, v45
	v_cndmask_b32_e32 v38, 0, v36, vcc
	v_cmp_lt_f32_e32 vcc, s33, v47
	v_cndmask_b32_e64 v46, v36, v38, s[8:9]
	s_nop 0
	v_cndmask_b32_e32 v39, 0, v37, vcc
	v_cndmask_b32_e64 v47, v37, v39, s[8:9]
	v_pk_fma_f32 v[38:39], v[48:49], s[12:13], v[104:105] op_sel_hi:[1,0,0]
	v_cmp_lt_f32_e32 vcc, s33, v48
	v_exp_f32_e32 v37, v38
	v_exp_f32_e32 v38, v39
	v_cvt_pk_bf16_f32 v36, v46, v47
	v_cndmask_b32_e32 v39, 0, v37, vcc
	v_cmp_lt_f32_e32 vcc, s33, v49
	v_cndmask_b32_e64 v48, v37, v39, s[8:9]
	s_nop 0
	v_cndmask_b32_e32 v40, 0, v38, vcc
	v_cndmask_b32_e64 v49, v38, v40, s[8:9]
	v_cvt_pk_bf16_f32 v37, v48, v49
	s_waitcnt lgkmcnt(0)
	s_nop 0
	v_mfma_f32_32x32x16_bf16 v[18:33], v[240:243], v[34:37], v[18:33]
	s_waitcnt lgkmcnt(0)
	v_mfma_f32_32x32x16_bf16 v[2:17], v[244:247], v[34:37], v[2:17]
	v_add_f32_e64 v34, v42, v52
	v_add_f32_e64 v35, v43, v53
	v_add_f32_e64 v34, v44, v34
	v_add_f32_e64 v35, v45, v35
	v_add_f32_e64 v34, v46, v34
	v_add_f32_e64 v35, v47, v35
	v_pk_add_f32 v[34:35], v[48:49], v[34:35]
	s_nop 0
	v_add_f32_e32 v34, v34, v35
	ds_bpermute_b32 v35, v165, v34
	s_cmp_ge_u32 s17, s18
	s_cbranch_scc1 .Ldma_m_mla2
	s_add_i32 s98, s6, 0xffffa800
	s_cmp_lg_u32 s44, 0
	s_cselect_b32 s98, s98, 0x10800
	s_add_i32 s98, s98, 0
	v_add_u32_e32 v247, s98, v107
	s_nop 0
	v_readfirstlane_b32 s99, v247
	v_add_u32_e32 v247, s98, v93
	s_mov_b32 m0, s99
	v_readfirstlane_b32 s99, v247
	v_add_u32_e32 v247, s98, v108
	global_load_lds_dwordx4 v[102:103], off
	s_mov_b32 m0, s99
	v_readfirstlane_b32 s98, v247
	global_load_lds_dwordx4 v[100:101], off
	s_mov_b32 m0, s98
	s_nop 0
	global_load_lds_dwordx4 v[98:99], off

; #define MFMA(a, b, c) __builtin_amdgcn_mfma_f32_32x32x16_bf16((a), (b), (c), 0, 0, 0)
; template <int N> DI void wait_vmcnt() { asm volatile("s_waitcnt vmcnt(%0)" ::"n"(N) : "memory"); }
;     ...
;   float mc = m * c2;
;   if (MODE == 2) mc = selbit ? mc : 1e30f;
;   const f32x2v c2v = {c2, c2}, mcv = {-mc, -mc};
;   f32x2v rs2 = {0.f, 0.f};
; #pragma unroll
;   for (int ks = 0; ks < 2; ++ks)
; #pragma unroll
;     for (int st = 0; st < 2; ++st) {
;       union { unsigned u[4]; bf16x8 v; } pf;
; #pragma unroll
;       for (int j = 0; j < 4; ++j) {
;         const int i0 = 8 * st + 2 * j;
;         f32x2v t = {S[ks][i0], S[ks][i0 + 1]};
;         t = __builtin_elementwise_fma(t, c2v, mcv);
;         f32x2v pv;
;         if (variant == 1) { pv = t; } else {
;         pv.x = __builtin_amdgcn_exp2f(t.x);
;         pv.y = __builtin_amdgcn_exp2f(t.y);
;         }
;         if (MODE != 0) {
;           if (need_mask) {
;             pv.x = (S[ks][i0] > -1e29f) ? pv.x : 0.f;
;             pv.y = (S[ks][i0 + 1] > -1e29f) ? pv.y : 0.f;
;           }
;         }
;         rs2 += pv;
;         pf.u[j] = __builtin_bit_cast(unsigned, __builtin_convertvector(pv, hwbf16x2));
;       }
; #pragma unroll
;       for (int d = 0; d < DV / 32; ++d) {
;         const char* vp = base + C::KBYTES + (d * 32 + lr) * C::VSTR + (ks * 32 + 16 * st + 4 * lh) * 2;
;         const s16x4 lo = *(const s16x4*)vp, hi = *(const s16x4*)(vp + 16);
;         const bf16x8 vf = __builtin_shufflevector(lo, hi, 0, 1, 2, 3, 4, 5, 6, 7);
;         O[d] = MFMA(vf, pf.v, O[d]);
;       }
;     }
;   float rs = rs2.x + rs2.y;
;   rs += __shfl_xor(rs, 32);
;     ...
;   asm volatile("s_waitcnt vmcnt(0)" ::: "memory");
; #pragma unroll
;   for (int t = 0; t < NST - 1; ++t)
;     if (t < ntile) FA_ISSUE(t, t)
;   int stage = 0;
;   for (int t = 0; t < ntile; ++t) {
;     int ahead = ((ntile < t + NST - 1) ? ntile : t + NST - 1) - (t + 1);
;     if (NST == 4 && ahead >= 2) wait_vmcnt<2 * NI>();
;     else if (ahead >= 1) wait_vmcnt<NI>();
;     else wait_vmcnt<0>();
;     raw_barrier();
;     if (t + NST - 1 < ntile) {
;       const int sn = (stage == 0) ? NST - 1 : stage - 1;
;       FA_ISSUE(t + NST - 1, sn)
.Lfast_mla2:
	v_mul_f32_e32 v104, 0xbe16c740, v104
	s_mov_b32 s12, 0x3e16c740
	v_pk_fma_f32 v[118:119], v[50:51], s[12:13], v[104:105] op_sel_hi:[1,0,0]
	v_exp_f32_e32 v126, v118
	v_exp_f32_e32 v127, v119
	v_pk_fma_f32 v[50:51], v[52:53], s[12:13], v[104:105] op_sel_hi:[1,0,0]
	v_exp_f32_e32 v128, v50
	v_exp_f32_e32 v129, v51
	v_cvt_pk_bf16_f32 v118, v126, v127
	v_pk_fma_f32 v[50:51], v[54:55], s[12:13], v[104:105] op_sel_hi:[1,0,0]
	v_exp_f32_e32 v130, v50
	v_exp_f32_e32 v131, v51
	v_cvt_pk_bf16_f32 v119, v128, v129
	v_pk_fma_f32 v[50:51], v[56:57], s[12:13], v[104:105] op_sel_hi:[1,0,0]
	v_exp_f32_e32 v56, v50
	v_exp_f32_e32 v57, v51
	v_cvt_pk_bf16_f32 v120, v130, v131
	v_cvt_pk_bf16_f32 v121, v56, v57
	s_waitcnt lgkmcnt(0)
	s_nop 0
	v_mfma_f32_32x32x16_bf16 v[18:33], v[216:219], v[118:121], v[18:33]
	s_waitcnt lgkmcnt(0)
	v_mfma_f32_32x32x16_bf16 v[2:17], v[220:223], v[118:121], v[2:17]
	v_add_f32_e64 v52, v126, 0
	v_add_f32_e64 v53, v127, 0
	v_add_f32_e64 v52, v128, v52
	v_add_f32_e64 v53, v129, v53
	v_add_f32_e64 v52, v130, v52
	v_add_f32_e64 v53, v131, v53
	v_pk_add_f32 v[118:119], v[56:57], v[52:53]
	v_pk_fma_f32 v[52:53], v[58:59], s[12:13], v[104:105] op_sel_hi:[1,0,0]
	v_exp_f32_e32 v120, v52
	v_exp_f32_e32 v121, v53
	v_pk_fma_f32 v[54:55], v[60:61], s[12:13], v[104:105] op_sel_hi:[1,0,0]
	v_exp_f32_e32 v60, v54
	v_exp_f32_e32 v61, v55
	v_cvt_pk_bf16_f32 v52, v120, v121
	v_pk_fma_f32 v[54:55], v[62:63], s[12:13], v[104:105] op_sel_hi:[1,0,0]
	v_exp_f32_e32 v62, v54
	v_exp_f32_e32 v63, v55
	v_cvt_pk_bf16_f32 v53, v60, v61
	v_pk_fma_f32 v[56:57], v[64:65], s[12:13], v[104:105] op_sel_hi:[1,0,0]
	v_exp_f32_e32 v64, v56
	v_exp_f32_e32 v65, v57
	v_cvt_pk_bf16_f32 v54, v62, v63
	v_cvt_pk_bf16_f32 v55, v64, v65
	s_nop 1
	v_mfma_f32_32x32x16_bf16 v[18:33], v[224:227], v[52:55], v[18:33]
	s_waitcnt lgkmcnt(0)
	v_mfma_f32_32x32x16_bf16 v[2:17], v[228:231], v[52:55], v[2:17]
	v_fma_f32 v54, v34, s12, v104
	v_fma_f32 v55, v35, s12, v104
	v_fma_f32 v56, v36, s12, v104
	v_fma_f32 v57, v37, s12, v104
	v_exp_f32_e32 v54, v54
	v_exp_f32_e32 v55, v55
	v_pk_add_f32 v[52:53], v[120:121], v[118:119]
	v_pk_add_f32 v[52:53], v[60:61], v[52:53]
	v_exp_f32_e32 v56, v56
	v_exp_f32_e32 v57, v57
	v_cvt_pk_bf16_f32 v34, v54, v55
	v_pk_add_f32 v[52:53], v[62:63], v[52:53]
	v_pk_add_f32 v[52:53], v[64:65], v[52:53]
	v_pk_fma_f32 v[36:37], v[38:39], s[12:13], v[104:105] op_sel_hi:[1,0,0]
	v_exp_f32_e32 v58, v36
	v_exp_f32_e32 v59, v37
	v_cvt_pk_bf16_f32 v35, v56, v57
	v_pk_fma_f32 v[38:39], v[40:41], s[12:13], v[104:105] op_sel_hi:[1,0,0]
	v_exp_f32_e32 v60, v38
	v_exp_f32_e32 v61, v39
	v_cvt_pk_bf16_f32 v36, v58, v59
	v_cvt_pk_bf16_f32 v37, v60, v61
	s_waitcnt lgkmcnt(0)
	s_nop 0
	v_mfma_f32_32x32x16_bf16 v[18:33], v[232:235], v[34:37], v[18:33]
	s_waitcnt lgkmcnt(0)
	v_mfma_f32_32x32x16_bf16 v[2:17], v[236:239], v[34:37], v[2:17]
	v_add_f32_e64 v34, v54, v52
	v_add_f32_e64 v35, v55, v53
	v_add_f32_e64 v34, v56, v34
	v_add_f32_e64 v35, v57, v35
	v_add_f32_e64 v34, v58, v34
	v_add_f32_e64 v35, v59, v35
	v_pk_add_f32 v[52:53], v[60:61], v[34:35]
	v_pk_fma_f32 v[34:35], v[42:43], s[12:13], v[104:105] op_sel_hi:[1,0,0]
	v_exp_f32_e32 v42, v34
	v_exp_f32_e32 v43, v35
	v_pk_fma_f32 v[36:37], v[44:45], s[12:13], v[104:105] op_sel_hi:[1,0,0]
	v_exp_f32_e32 v44, v36
	v_exp_f32_e32 v45, v37
	v_cvt_pk_bf16_f32 v34, v42, v43
	v_pk_fma_f32 v[36:37], v[46:47], s[12:13], v[104:105] op_sel_hi:[1,0,0]
	v_exp_f32_e32 v46, v36
	v_exp_f32_e32 v47, v37
	v_cvt_pk_bf16_f32 v35, v44, v45
	v_pk_fma_f32 v[38:39], v[48:49], s[12:13], v[104:105] op_sel_hi:[1,0,0]
	v_exp_f32_e32 v48, v38
	v_exp_f32_e32 v49, v39
	v_cvt_pk_bf16_f32 v36, v46, v47
	v_cvt_pk_bf16_f32 v37, v48, v49
	s_waitcnt lgkmcnt(0)
	s_nop 0
	v_mfma_f32_32x32x16_bf16 v[18:33], v[240:243], v[34:37], v[18:33]
	s_waitcnt lgkmcnt(0)
	v_mfma_f32_32x32x16_bf16 v[2:17], v[244:247], v[34:37], v[2:17]
	v_add_f32_e64 v34, v42, v52
	v_add_f32_e64 v35, v43, v53
	v_add_f32_e64 v34, v44, v34
	v_add_f32_e64 v35, v45, v35
	v_add_f32_e64 v34, v46, v34
	v_add_f32_e64 v35, v47, v35
	v_pk_add_f32 v[34:35], v[48:49], v[34:35]
	v_add_f32_e32 v34, v34, v35
	ds_bpermute_b32 v35, v165, v34
	s_cmp_ge_u32 s17, s18
	s_cbranch_scc1 .Ldma_f_mla2
	s_add_i32 s98, s6, 0xffffa800
	s_cmp_lg_u32 s44, 0
	s_cselect_b32 s98, s98, 0x10800
	s_add_i32 s98, s98, 0
	v_add_u32_e32 v247, s98, v107
	s_nop 0
	v_readfirstlane_b32 s99, v247
	v_add_u32_e32 v247, s98, v93
	s_mov_b32 m0, s99
	v_readfirstlane_b32 s99, v247
	v_add_u32_e32 v247, s98, v108
	global_load_lds_dwordx4 v[102:103], off
	s_mov_b32 m0, s99
	v_readfirstlane_b32 s98, v247
	global_load_lds_dwordx4 v[100:101], off
	s_mov_b32 m0, s98
	s_nop 0
	global_load_lds_dwordx4 v[98:99], off

; #define MFMA(a, b, c) __builtin_amdgcn_mfma_f32_32x32x16_bf16((a), (b), (c), 0, 0, 0)
;     ...
;   float mc = m * c2;
;   if (MODE == 2) mc = selbit ? mc : 1e30f;
;   const f32x2v c2v = {c2, c2}, mcv = {-mc, -mc};
;   f32x2v rs2 = {0.f, 0.f};
; #pragma unroll
;   for (int ks = 0; ks < 2; ++ks)
; #pragma unroll
;     for (int st = 0; st < 2; ++st) {
;       union { unsigned u[4]; bf16x8 v; } pf;
; #pragma unroll
;       for (int j = 0; j < 4; ++j) {
;         const int i0 = 8 * st + 2 * j;
;         f32x2v t = {S[ks][i0], S[ks][i0 + 1]};
;         t = __builtin_elementwise_fma(t, c2v, mcv);
;         f32x2v pv;
;         if (variant == 1) { pv = t; } else {
;         pv.x = __builtin_amdgcn_exp2f(t.x);
;         pv.y = __builtin_amdgcn_exp2f(t.y);
;         }
;         if (MODE != 0) {
;           if (need_mask) {
;             pv.x = (S[ks][i0] > -1e29f) ? pv.x : 0.f;
;             pv.y = (S[ks][i0 + 1] > -1e29f) ? pv.y : 0.f;
;           }
;         }
;         rs2 += pv;
;         pf.u[j] = __builtin_bit_cast(unsigned, __builtin_convertvector(pv, hwbf16x2));
;       }
; #pragma unroll
;       for (int d = 0; d < DV / 32; ++d) {
;         const char* vp = base + C::KBYTES + (d * 32 + lr) * C::VSTR + (ks * 32 + 16 * st + 4 * lh) * 2;
;         const s16x4 lo = *(const s16x4*)vp, hi = *(const s16x4*)(vp + 16);
;         const bf16x8 vf = __builtin_shufflevector(lo, hi, 0, 1, 2, 3, 4, 5, 6, 7);
;         O[d] = MFMA(vf, pf.v, O[d]);
;       }
;     }
.LBB0_549:
	s_cmp_eq_u64 s[8:9], 0
	s_cbranch_scc1 .Lfast_sel2
	v_mul_f32_e32 v14, 0xbe38aa3b, v14
	v_cndmask_b32_e64 v14, v208, v14, s[10:11]
	v_pk_fma_f32 v[120:121], v[96:97], s[96:97], v[14:15] op_sel_hi:[1,0,0]
	v_cmp_lt_f32_e32 vcc, s33, v96
	v_exp_f32_e32 v119, v120
	v_exp_f32_e32 v120, v121
	v_cndmask_b32_e32 v96, 0, v119, vcc
	v_cmp_lt_f32_e32 vcc, s33, v97
	v_cndmask_b32_e64 v128, v119, v96, s[8:9]
	s_nop 0
	v_cndmask_b32_e32 v97, 0, v120, vcc
	v_cndmask_b32_e64 v129, v120, v97, s[8:9]
	v_pk_fma_f32 v[96:97], v[98:99], s[96:97], v[14:15] op_sel_hi:[1,0,0]
	v_cmp_lt_f32_e32 vcc, s33, v98
	v_exp_f32_e32 v96, v96
	v_exp_f32_e32 v97, v97
	v_cvt_pk_bf16_f32 v120, v128, v129
	v_cndmask_b32_e32 v98, 0, v96, vcc
	v_cmp_lt_f32_e32 vcc, s33, v99
	v_cndmask_b32_e64 v130, v96, v98, s[8:9]
	s_nop 0
	v_cndmask_b32_e32 v99, 0, v97, vcc
	v_cndmask_b32_e64 v131, v97, v99, s[8:9]
	v_pk_fma_f32 v[96:97], v[100:101], s[96:97], v[14:15] op_sel_hi:[1,0,0]
	v_cmp_lt_f32_e32 vcc, s33, v100
	v_exp_f32_e32 v96, v96
	v_exp_f32_e32 v97, v97
	v_cvt_pk_bf16_f32 v121, v130, v131
	v_cndmask_b32_e32 v98, 0, v96, vcc
	v_cmp_lt_f32_e32 vcc, s33, v101
	v_cndmask_b32_e64 v132, v96, v98, s[8:9]
	s_nop 0
	v_cndmask_b32_e32 v99, 0, v97, vcc
	v_cndmask_b32_e64 v133, v97, v99, s[8:9]
	v_pk_fma_f32 v[96:97], v[102:103], s[96:97], v[14:15] op_sel_hi:[1,0,0]
	v_cmp_lt_f32_e32 vcc, s33, v102
	v_exp_f32_e32 v96, v96
	v_exp_f32_e32 v97, v97
	v_cvt_pk_bf16_f32 v122, v132, v133
	v_cndmask_b32_e32 v98, 0, v96, vcc
	v_cmp_lt_f32_e32 vcc, s33, v103
	v_cndmask_b32_e64 v102, v96, v98, s[8:9]
	s_nop 0
	v_cndmask_b32_e32 v99, 0, v97, vcc
	v_cndmask_b32_e64 v103, v97, v99, s[8:9]
	s_nop 0
	s_nop 0
	s_nop 0
	s_nop 0
	v_cvt_pk_bf16_f32 v123, v102, v103
	s_nop 0
	v_cmp_lt_f32_e32 vcc, s33, v104
	s_waitcnt lgkmcnt(0)
	v_mfma_f32_32x32x16_bf16 v[64:79], v[216:219], v[120:123], v[64:79]
	s_nop 0
	s_waitcnt lgkmcnt(0)
	v_mfma_f32_32x32x16_bf16 v[48:63], v[220:223], v[120:123], v[48:63]
	v_add_f32_e64 v98, v128, 0
	v_add_f32_e64 v99, v129, 0
	v_add_f32_e64 v98, v130, v98
	v_add_f32_e64 v99, v131, v99
	v_add_f32_e64 v98, v132, v98
	v_add_f32_e64 v99, v133, v99
	v_pk_add_f32 v[120:121], v[102:103], v[98:99]
	v_pk_fma_f32 v[98:99], v[104:105], s[96:97], v[14:15] op_sel_hi:[1,0,0]
	s_nop 0
	v_exp_f32_e32 v98, v98
	v_exp_f32_e32 v99, v99
	v_cndmask_b32_e32 v100, 0, v98, vcc
	v_cmp_lt_f32_e32 vcc, s33, v105
	v_cndmask_b32_e64 v122, v98, v100, s[8:9]
	s_nop 0
	v_cndmask_b32_e32 v101, 0, v99, vcc
	v_cndmask_b32_e64 v123, v99, v101, s[8:9]
	v_pk_fma_f32 v[100:101], v[106:107], s[96:97], v[14:15] op_sel_hi:[1,0,0]
	v_cmp_lt_f32_e32 vcc, s33, v106
	v_exp_f32_e32 v99, v100
	v_exp_f32_e32 v100, v101
	v_cvt_pk_bf16_f32 v98, v122, v123
	v_cndmask_b32_e32 v101, 0, v99, vcc
	v_cmp_lt_f32_e32 vcc, s33, v107
	v_cndmask_b32_e64 v106, v99, v101, s[8:9]
	s_nop 0
	v_cndmask_b32_e32 v102, 0, v100, vcc
	v_cndmask_b32_e64 v107, v100, v102, s[8:9]
	v_pk_fma_f32 v[100:101], v[108:109], s[96:97], v[14:15] op_sel_hi:[1,0,0]
	v_cmp_lt_f32_e32 vcc, s33, v108
	v_exp_f32_e32 v100, v100
	v_exp_f32_e32 v101, v101
	v_cvt_pk_bf16_f32 v99, v106, v107
	v_cndmask_b32_e32 v102, 0, v100, vcc
	v_cmp_lt_f32_e32 vcc, s33, v109
	v_cndmask_b32_e64 v108, v100, v102, s[8:9]
	s_nop 0
	v_cndmask_b32_e32 v103, 0, v101, vcc
	v_cndmask_b32_e64 v109, v101, v103, s[8:9]
	v_pk_fma_f32 v[102:103], v[110:111], s[96:97], v[14:15] op_sel_hi:[1,0,0]
	v_cmp_lt_f32_e32 vcc, s33, v110
	v_exp_f32_e32 v101, v102
	v_exp_f32_e32 v102, v103
	v_cvt_pk_bf16_f32 v100, v108, v109
	v_cndmask_b32_e32 v103, 0, v101, vcc
	v_cmp_lt_f32_e32 vcc, s33, v111
	v_cndmask_b32_e64 v110, v101, v103, s[8:9]
	s_nop 0
	v_cndmask_b32_e32 v104, 0, v102, vcc
	v_cndmask_b32_e64 v111, v102, v104, s[8:9]
	s_nop 0
	v_cvt_pk_bf16_f32 v101, v110, v111
	v_cmp_lt_f32_e32 vcc, s33, v80
	s_nop 0
	v_mfma_f32_32x32x16_bf16 v[64:79], v[224:227], v[98:101], v[64:79]
	s_waitcnt lgkmcnt(0)
	v_mfma_f32_32x32x16_bf16 v[48:63], v[228:231], v[98:101], v[48:63]
	v_fma_f32 v100, v80, s96, v14
	v_fma_f32 v101, v81, s96, v14
	v_fma_f32 v102, v82, s96, v14
	v_fma_f32 v103, v83, s96, v14
	v_exp_f32_e32 v100, v100
	v_exp_f32_e32 v101, v101
	v_pk_add_f32 v[98:99], v[122:123], v[120:121]
	v_cndmask_b32_e32 v80, 0, v100, vcc
	v_cmp_lt_f32_e32 vcc, s33, v81
	v_pk_add_f32 v[98:99], v[106:107], v[98:99]
	v_cndmask_b32_e64 v100, v100, v80, s[8:9]
	v_cndmask_b32_e32 v81, 0, v101, vcc
	v_cndmask_b32_e64 v101, v101, v81, s[8:9]
	v_exp_f32_e32 v81, v102
	v_exp_f32_e32 v102, v103
	v_cmp_lt_f32_e32 vcc, s33, v82
	v_cvt_pk_bf16_f32 v80, v100, v101
	v_pk_add_f32 v[98:99], v[108:109], v[98:99]
	v_cndmask_b32_e32 v82, 0, v81, vcc
	v_cmp_lt_f32_e32 vcc, s33, v83
	v_pk_add_f32 v[98:99], v[110:111], v[98:99]
	s_nop 0
	v_cndmask_b32_e32 v83, 0, v102, vcc
	v_cndmask_b32_e64 v103, v102, v83, s[8:9]
	v_cndmask_b32_e64 v102, v81, v82, s[8:9]
	v_pk_fma_f32 v[82:83], v[84:85], s[96:97], v[14:15] op_sel_hi:[1,0,0]
	v_cmp_lt_f32_e32 vcc, s33, v84
	v_exp_f32_e32 v82, v82
	v_exp_f32_e32 v83, v83
	v_cvt_pk_bf16_f32 v81, v102, v103
	v_cndmask_b32_e32 v84, 0, v82, vcc
	v_cmp_lt_f32_e32 vcc, s33, v85
	v_cndmask_b32_e64 v104, v82, v84, s[8:9]
	s_nop 0
	v_cndmask_b32_e32 v85, 0, v83, vcc
	v_cndmask_b32_e64 v105, v83, v85, s[8:9]
	v_pk_fma_f32 v[84:85], v[86:87], s[96:97], v[14:15] op_sel_hi:[1,0,0]
	v_cmp_lt_f32_e32 vcc, s33, v86
	v_exp_f32_e32 v83, v84
	v_exp_f32_e32 v84, v85
	v_cvt_pk_bf16_f32 v82, v104, v105
	v_cndmask_b32_e32 v85, 0, v83, vcc
	v_cmp_lt_f32_e32 vcc, s33, v87
	v_cndmask_b32_e64 v106, v83, v85, s[8:9]
	s_nop 0
	v_cndmask_b32_e32 v86, 0, v84, vcc
	v_cndmask_b32_e64 v107, v84, v86, s[8:9]
	s_nop 0
	v_cvt_pk_bf16_f32 v83, v106, v107
	v_cmp_lt_f32_e32 vcc, s33, v88
	s_waitcnt lgkmcnt(0)
; #define MFMA(a, b, c) __builtin_amdgcn_mfma_f32_32x32x16_bf16((a), (b), (c), 0, 0, 0)
; template <int N> DI void wait_vmcnt() { asm volatile("s_waitcnt vmcnt(%0)" ::"n"(N) : "memory"); }
;     ...
; #pragma unroll
;       for (int j = 0; j < 4; ++j) {
;         const int i0 = 8 * st + 2 * j;
;         f32x2v t = {S[ks][i0], S[ks][i0 + 1]};
;         t = __builtin_elementwise_fma(t, c2v, mcv);
;         f32x2v pv;
;         if (variant == 1) { pv = t; } else {
;         pv.x = __builtin_amdgcn_exp2f(t.x);
;         pv.y = __builtin_amdgcn_exp2f(t.y);
;         }
;         if (MODE != 0) {
;           if (need_mask) {
;             pv.x = (S[ks][i0] > -1e29f) ? pv.x : 0.f;
;             pv.y = (S[ks][i0 + 1] > -1e29f) ? pv.y : 0.f;
;           }
;         }
;         rs2 += pv;
;         pf.u[j] = __builtin_bit_cast(unsigned, __builtin_convertvector(pv, hwbf16x2));
;       }
; #pragma unroll
;       for (int d = 0; d < DV / 32; ++d) {
;         const char* vp = base + C::KBYTES + (d * 32 + lr) * C::VSTR + (ks * 32 + 16 * st + 4 * lh) * 2;
;         const s16x4 lo = *(const s16x4*)vp, hi = *(const s16x4*)(vp + 16);
;         const bf16x8 vf = __builtin_shufflevector(lo, hi, 0, 1, 2, 3, 4, 5, 6, 7);
;         O[d] = MFMA(vf, pf.v, O[d]);
;       }
;     }
;   float rs = rs2.x + rs2.y;
;   rs += __shfl_xor(rs, 32);
;   l += rs;
;     ...
;   asm volatile("s_waitcnt vmcnt(0)" ::: "memory");
; #pragma unroll
;   for (int t = 0; t < NST - 1; ++t)
;     if (t < ntile) FA_ISSUE(t, t)
;   int stage = 0;
;   for (int t = 0; t < ntile; ++t) {
;     int ahead = ((ntile < t + NST - 1) ? ntile : t + NST - 1) - (t + 1);
;     if (NST == 4 && ahead >= 2) wait_vmcnt<2 * NI>();
;     else if (ahead >= 1) wait_vmcnt<NI>();
;     else wait_vmcnt<0>();
;     raw_barrier();
;     if (t + NST - 1 < ntile) {
;       const int sn = (stage == 0) ? NST - 1 : stage - 1;
;       FA_ISSUE(t + NST - 1, sn)
	v_mfma_f32_32x32x16_bf16 v[64:79], v[232:235], v[80:83], v[64:79]
	s_nop 0
	s_waitcnt lgkmcnt(0)
	v_mfma_f32_32x32x16_bf16 v[48:63], v[236:239], v[80:83], v[48:63]
	v_add_f32_e64 v80, v100, v98
	v_add_f32_e64 v81, v101, v99
	v_add_f32_e64 v80, v102, v80
	v_add_f32_e64 v81, v103, v81
	v_add_f32_e64 v80, v104, v80
	v_add_f32_e64 v81, v105, v81
	v_pk_add_f32 v[98:99], v[106:107], v[80:81]
	v_pk_fma_f32 v[80:81], v[88:89], s[96:97], v[14:15] op_sel_hi:[1,0,0]
	s_nop 0
	v_exp_f32_e32 v80, v80
	v_exp_f32_e32 v81, v81
	v_cndmask_b32_e32 v82, 0, v80, vcc
	v_cmp_lt_f32_e32 vcc, s33, v89
	v_cndmask_b32_e64 v88, v80, v82, s[8:9]
	s_nop 0
	v_cndmask_b32_e32 v83, 0, v81, vcc
	v_cndmask_b32_e64 v89, v81, v83, s[8:9]
	v_pk_fma_f32 v[82:83], v[90:91], s[96:97], v[14:15] op_sel_hi:[1,0,0]
	v_cmp_lt_f32_e32 vcc, s33, v90
	v_exp_f32_e32 v81, v82
	v_exp_f32_e32 v82, v83
	v_cvt_pk_bf16_f32 v80, v88, v89
	v_cndmask_b32_e32 v83, 0, v81, vcc
	v_cmp_lt_f32_e32 vcc, s33, v91
	v_cndmask_b32_e64 v90, v81, v83, s[8:9]
	s_nop 0
	v_cndmask_b32_e32 v84, 0, v82, vcc
	v_cndmask_b32_e64 v91, v82, v84, s[8:9]
	v_pk_fma_f32 v[82:83], v[92:93], s[96:97], v[14:15] op_sel_hi:[1,0,0]
	v_cmp_lt_f32_e32 vcc, s33, v92
	v_exp_f32_e32 v82, v82
	v_exp_f32_e32 v83, v83
	v_cvt_pk_bf16_f32 v81, v90, v91
	v_cndmask_b32_e32 v84, 0, v82, vcc
	v_cmp_lt_f32_e32 vcc, s33, v93
	v_cndmask_b32_e64 v92, v82, v84, s[8:9]
	s_nop 0
	v_cndmask_b32_e32 v85, 0, v83, vcc
	v_cndmask_b32_e64 v93, v83, v85, s[8:9]
	v_pk_fma_f32 v[84:85], v[94:95], s[96:97], v[14:15] op_sel_hi:[1,0,0]
	v_cmp_lt_f32_e32 vcc, s33, v94
	v_exp_f32_e32 v14, v84
	v_exp_f32_e32 v83, v85
	v_cvt_pk_bf16_f32 v82, v92, v93
	v_cndmask_b32_e32 v84, 0, v14, vcc
	v_cmp_lt_f32_e32 vcc, s33, v95
	v_cndmask_b32_e64 v94, v14, v84, s[8:9]
	s_nop 0
	v_cndmask_b32_e32 v85, 0, v83, vcc
	v_cndmask_b32_e64 v95, v83, v85, s[8:9]
	s_nop 0
	v_cvt_pk_bf16_f32 v83, v94, v95
	s_waitcnt lgkmcnt(0)
	s_nop 0
	v_mfma_f32_32x32x16_bf16 v[64:79], v[240:243], v[80:83], v[64:79]
	s_nop 0
	s_waitcnt lgkmcnt(0)
	v_mfma_f32_32x32x16_bf16 v[48:63], v[244:247], v[80:83], v[48:63]
	v_add_f32_e64 v80, v88, v98
	v_add_f32_e64 v81, v89, v99
	v_add_f32_e64 v80, v90, v80
	v_add_f32_e64 v81, v91, v81
	v_add_f32_e64 v80, v92, v80
	v_add_f32_e64 v81, v93, v81
	v_pk_add_f32 v[80:81], v[94:95], v[80:81]
	s_nop 0
	v_add_f32_e32 v14, v80, v81
	ds_bpermute_b32 v80, v165, v14
	s_add_i32 s98, s0, 3
	s_cmp_gt_u32 s98, s41
	s_cbranch_scc1 .Ldma_m_sel2
	s_add_i32 s98, s6, 0xffffb800
	s_cmp_lg_u32 s45, 0
	s_cselect_b32 s98, s98, 0xd800
	s_add_i32 s98, s98, 0
	v_add_u32_e32 v247, s98, v112
	s_nop 0
	v_readfirstlane_b32 s99, v247
	v_add_u32_e32 v247, s98, v15
	s_mov_b32 m0, s99
	v_readfirstlane_b32 s99, v247
	v_add_u32_e32 v247, s98, v113
	global_load_lds_dwordx4 v[12:13], off
	s_mov_b32 m0, s99
	v_readfirstlane_b32 s98, v247
	global_load_lds_dwordx4 v[10:11], off
	s_mov_b32 m0, s98
	s_nop 0
	global_load_lds_dwordx4 v[8:9], off
.Ldma_m_sel2:
	s_waitcnt lgkmcnt(0)
	v_add_f32_e32 v14, v14, v80
	v_add_f32_e32 v168, v168, v14
	s_branch .Ldma_skip_sel2
; #define MFMA(a, b, c) __builtin_amdgcn_mfma_f32_32x32x16_bf16((a), (b), (c), 0, 0, 0)
; template <int N> DI void wait_vmcnt() { asm volatile("s_waitcnt vmcnt(%0)" ::"n"(N) : "memory"); }
;     ...
;   float mc = m * c2;
;   if (MODE == 2) mc = selbit ? mc : 1e30f;
;   const f32x2v c2v = {c2, c2}, mcv = {-mc, -mc};
;   f32x2v rs2 = {0.f, 0.f};
; #pragma unroll
;   for (int ks = 0; ks < 2; ++ks)
; #pragma unroll
;     for (int st = 0; st < 2; ++st) {
;       union { unsigned u[4]; bf16x8 v; } pf;
; #pragma unroll
;       for (int j = 0; j < 4; ++j) {
;         const int i0 = 8 * st + 2 * j;
;         f32x2v t = {S[ks][i0], S[ks][i0 + 1]};
;         t = __builtin_elementwise_fma(t, c2v, mcv);
;         f32x2v pv;
;         if (variant == 1) { pv = t; } else {
;         pv.x = __builtin_amdgcn_exp2f(t.x);
;         pv.y = __builtin_amdgcn_exp2f(t.y);
;         }
;         if (MODE != 0) {
;           if (need_mask) {
;             pv.x = (S[ks][i0] > -1e29f) ? pv.x : 0.f;
;             pv.y = (S[ks][i0 + 1] > -1e29f) ? pv.y : 0.f;
;           }
;         }
;         rs2 += pv;
;         pf.u[j] = __builtin_bit_cast(unsigned, __builtin_convertvector(pv, hwbf16x2));
;       }
; #pragma unroll
;       for (int d = 0; d < DV / 32; ++d) {
;         const char* vp = base + C::KBYTES + (d * 32 + lr) * C::VSTR + (ks * 32 + 16 * st + 4 * lh) * 2;
;         const s16x4 lo = *(const s16x4*)vp, hi = *(const s16x4*)(vp + 16);
;         const bf16x8 vf = __builtin_shufflevector(lo, hi, 0, 1, 2, 3, 4, 5, 6, 7);
;         O[d] = MFMA(vf, pf.v, O[d]);
;       }
;     }
;   float rs = rs2.x + rs2.y;
;   rs += __shfl_xor(rs, 32);
;     ...
;   asm volatile("s_waitcnt vmcnt(0)" ::: "memory");
; #pragma unroll
;   for (int t = 0; t < NST - 1; ++t)
;     if (t < ntile) FA_ISSUE(t, t)
;   int stage = 0;
;   for (int t = 0; t < ntile; ++t) {
;     int ahead = ((ntile < t + NST - 1) ? ntile : t + NST - 1) - (t + 1);
;     if (NST == 4 && ahead >= 2) wait_vmcnt<2 * NI>();
;     else if (ahead >= 1) wait_vmcnt<NI>();
;     else wait_vmcnt<0>();
;     raw_barrier();
;     if (t + NST - 1 < ntile) {
;       const int sn = (stage == 0) ? NST - 1 : stage - 1;
;       FA_ISSUE(t + NST - 1, sn)
.Lfast_sel2:
	v_mul_f32_e32 v14, 0xbe38aa3b, v14
	v_cndmask_b32_e64 v14, v208, v14, s[10:11]
	v_pk_fma_f32 v[120:121], v[96:97], s[96:97], v[14:15] op_sel_hi:[1,0,0]
	v_exp_f32_e32 v128, v120
	v_exp_f32_e32 v129, v121
	v_pk_fma_f32 v[96:97], v[98:99], s[96:97], v[14:15] op_sel_hi:[1,0,0]
	v_exp_f32_e32 v130, v96
	v_exp_f32_e32 v131, v97
	v_cvt_pk_bf16_f32 v120, v128, v129
	v_pk_fma_f32 v[96:97], v[100:101], s[96:97], v[14:15] op_sel_hi:[1,0,0]
	v_exp_f32_e32 v132, v96
	v_exp_f32_e32 v133, v97
	v_cvt_pk_bf16_f32 v121, v130, v131
	v_pk_fma_f32 v[96:97], v[102:103], s[96:97], v[14:15] op_sel_hi:[1,0,0]
	v_exp_f32_e32 v102, v96
	v_exp_f32_e32 v103, v97
	v_cvt_pk_bf16_f32 v122, v132, v133
	v_cvt_pk_bf16_f32 v123, v102, v103
	s_waitcnt lgkmcnt(0)
	s_nop 0
	v_mfma_f32_32x32x16_bf16 v[64:79], v[216:219], v[120:123], v[64:79]
	s_waitcnt lgkmcnt(0)
	v_mfma_f32_32x32x16_bf16 v[48:63], v[220:223], v[120:123], v[48:63]
	v_add_f32_e64 v98, v128, 0
	v_add_f32_e64 v99, v129, 0
	v_add_f32_e64 v98, v130, v98
	v_add_f32_e64 v99, v131, v99
	v_add_f32_e64 v98, v132, v98
	v_add_f32_e64 v99, v133, v99
	v_pk_add_f32 v[120:121], v[102:103], v[98:99]
	v_pk_fma_f32 v[98:99], v[104:105], s[96:97], v[14:15] op_sel_hi:[1,0,0]
	v_exp_f32_e32 v122, v98
	v_exp_f32_e32 v123, v99
	v_pk_fma_f32 v[100:101], v[106:107], s[96:97], v[14:15] op_sel_hi:[1,0,0]
	v_exp_f32_e32 v106, v100
	v_exp_f32_e32 v107, v101
	v_cvt_pk_bf16_f32 v98, v122, v123
	v_pk_fma_f32 v[100:101], v[108:109], s[96:97], v[14:15] op_sel_hi:[1,0,0]
	v_exp_f32_e32 v108, v100
	v_exp_f32_e32 v109, v101
	v_cvt_pk_bf16_f32 v99, v106, v107
	v_pk_fma_f32 v[102:103], v[110:111], s[96:97], v[14:15] op_sel_hi:[1,0,0]
	v_exp_f32_e32 v110, v102
	v_exp_f32_e32 v111, v103
	v_cvt_pk_bf16_f32 v100, v108, v109
	v_cvt_pk_bf16_f32 v101, v110, v111
	s_nop 1
	v_mfma_f32_32x32x16_bf16 v[64:79], v[224:227], v[98:101], v[64:79]
	s_waitcnt lgkmcnt(0)
	v_mfma_f32_32x32x16_bf16 v[48:63], v[228:231], v[98:101], v[48:63]
	v_fma_f32 v100, v80, s96, v14
	v_fma_f32 v101, v81, s96, v14
	v_fma_f32 v102, v82, s96, v14
	v_fma_f32 v103, v83, s96, v14
	v_exp_f32_e32 v100, v100
	v_exp_f32_e32 v101, v101
	v_pk_add_f32 v[98:99], v[122:123], v[120:121]
	v_pk_add_f32 v[98:99], v[106:107], v[98:99]
	v_exp_f32_e32 v102, v102
	v_exp_f32_e32 v103, v103
	v_cvt_pk_bf16_f32 v80, v100, v101
	v_pk_add_f32 v[98:99], v[108:109], v[98:99]
	v_pk_add_f32 v[98:99], v[110:111], v[98:99]
	v_pk_fma_f32 v[82:83], v[84:85], s[96:97], v[14:15] op_sel_hi:[1,0,0]
	v_exp_f32_e32 v104, v82
	v_exp_f32_e32 v105, v83
	v_cvt_pk_bf16_f32 v81, v102, v103
	v_pk_fma_f32 v[84:85], v[86:87], s[96:97], v[14:15] op_sel_hi:[1,0,0]
	v_exp_f32_e32 v106, v84
	v_exp_f32_e32 v107, v85
	v_cvt_pk_bf16_f32 v82, v104, v105
	v_cvt_pk_bf16_f32 v83, v106, v107
	s_waitcnt lgkmcnt(0)
	s_nop 0
	v_mfma_f32_32x32x16_bf16 v[64:79], v[232:235], v[80:83], v[64:79]
	s_waitcnt lgkmcnt(0)
	v_mfma_f32_32x32x16_bf16 v[48:63], v[236:239], v[80:83], v[48:63]
	v_add_f32_e64 v80, v100, v98
	v_add_f32_e64 v81, v101, v99
	v_add_f32_e64 v80, v102, v80
	v_add_f32_e64 v81, v103, v81
	v_add_f32_e64 v80, v104, v80
	v_add_f32_e64 v81, v105, v81
	v_pk_add_f32 v[98:99], v[106:107], v[80:81]
	v_pk_fma_f32 v[80:81], v[88:89], s[96:97], v[14:15] op_sel_hi:[1,0,0]
	v_exp_f32_e32 v88, v80
	v_exp_f32_e32 v89, v81
	v_pk_fma_f32 v[82:83], v[90:91], s[96:97], v[14:15] op_sel_hi:[1,0,0]
	v_exp_f32_e32 v90, v82
	v_exp_f32_e32 v91, v83
	v_cvt_pk_bf16_f32 v80, v88, v89
	v_pk_fma_f32 v[82:83], v[92:93], s[96:97], v[14:15] op_sel_hi:[1,0,0]
	v_exp_f32_e32 v92, v82
	v_exp_f32_e32 v93, v83
	v_cvt_pk_bf16_f32 v81, v90, v91
	v_pk_fma_f32 v[84:85], v[94:95], s[96:97], v[14:15] op_sel_hi:[1,0,0]
	v_exp_f32_e32 v94, v84
	v_exp_f32_e32 v95, v85
	v_cvt_pk_bf16_f32 v82, v92, v93
	v_cvt_pk_bf16_f32 v83, v94, v95
	s_waitcnt lgkmcnt(0)
	s_nop 0
	v_mfma_f32_32x32x16_bf16 v[64:79], v[240:243], v[80:83], v[64:79]
	s_waitcnt lgkmcnt(0)
	v_mfma_f32_32x32x16_bf16 v[48:63], v[244:247], v[80:83], v[48:63]
	v_add_f32_e64 v80, v88, v98
	v_add_f32_e64 v81, v89, v99
	v_add_f32_e64 v80, v90, v80
	v_add_f32_e64 v81, v91, v81
	v_add_f32_e64 v80, v92, v80
	v_add_f32_e64 v81, v93, v81
	v_pk_add_f32 v[80:81], v[94:95], v[80:81]
	v_add_f32_e32 v14, v80, v81
	ds_bpermute_b32 v80, v165, v14
	s_add_i32 s98, s0, 3
	s_cmp_gt_u32 s98, s41
	s_cbranch_scc1 .Ldma_f_sel2
	s_add_i32 s98, s6, 0xffffb800
	s_cmp_lg_u32 s45, 0
	s_cselect_b32 s98, s98, 0xd800
	s_add_i32 s98, s98, 0
	v_add_u32_e32 v247, s98, v112
	s_nop 0
	v_readfirstlane_b32 s99, v247
	v_add_u32_e32 v247, s98, v15
	s_mov_b32 m0, s99
	v_readfirstlane_b32 s99, v247
	v_add_u32_e32 v247, s98, v113
	global_load_lds_dwordx4 v[12:13], off
	s_mov_b32 m0, s99
	v_readfirstlane_b32 s98, v247
	global_load_lds_dwordx4 v[10:11], off
	s_mov_b32 m0, s98
	s_nop 0
	global_load_lds_dwordx4 v[8:9], off

; #define MFMA(a, b, c) __builtin_amdgcn_mfma_f32_32x32x16_bf16((a), (b), (c), 0, 0, 0)
;     ...
;   float mc = m * c2;
;   if (MODE == 2) mc = selbit ? mc : 1e30f;
;   const f32x2v c2v = {c2, c2}, mcv = {-mc, -mc};
;   f32x2v rs2 = {0.f, 0.f};
; #pragma unroll
;   for (int ks = 0; ks < 2; ++ks)
; #pragma unroll
;     for (int st = 0; st < 2; ++st) {
;       union { unsigned u[4]; bf16x8 v; } pf;
; #pragma unroll
;       for (int j = 0; j < 4; ++j) {
;         const int i0 = 8 * st + 2 * j;
;         f32x2v t = {S[ks][i0], S[ks][i0 + 1]};
;         t = __builtin_elementwise_fma(t, c2v, mcv);
;         f32x2v pv;
;         if (variant == 1) { pv = t; } else {
;         pv.x = __builtin_amdgcn_exp2f(t.x);
;         pv.y = __builtin_amdgcn_exp2f(t.y);
;         }
;         if (MODE != 0) {
;           if (need_mask) {
;             pv.x = (S[ks][i0] > -1e29f) ? pv.x : 0.f;
;             pv.y = (S[ks][i0 + 1] > -1e29f) ? pv.y : 0.f;
;           }
;         }
;         rs2 += pv;
;         pf.u[j] = __builtin_bit_cast(unsigned, __builtin_convertvector(pv, hwbf16x2));
;       }
; #pragma unroll
;       for (int d = 0; d < DV / 32; ++d) {
;         const char* vp = base + C::KBYTES + (d * 32 + lr) * C::VSTR + (ks * 32 + 16 * st + 4 * lh) * 2;
;         const s16x4 lo = *(const s16x4*)vp, hi = *(const s16x4*)(vp + 16);
;         const bf16x8 vf = __builtin_shufflevector(lo, hi, 0, 1, 2, 3, 4, 5, 6, 7);
;         O[d] = MFMA(vf, pf.v, O[d]);
;       }
;     }
.LBB0_585:
	s_cmp_eq_u64 s[8:9], 0
	s_cbranch_scc1 .Lfast_win2
	v_mul_f32_e32 v12, 0xbe38aa3b, v12
	v_pk_fma_f32 v[176:177], v[128:129], s[96:97], v[12:13] op_sel_hi:[1,0,0]
	v_cmp_lt_f32_e32 vcc, s33, v128
	v_exp_f32_e32 v176, v176
	v_exp_f32_e32 v177, v177
	v_cndmask_b32_e32 v128, 0, v176, vcc
	v_cmp_lt_f32_e32 vcc, s33, v129
	v_cndmask_b32_e64 v184, v176, v128, s[8:9]
	s_nop 0
	v_cndmask_b32_e32 v129, 0, v177, vcc
	v_cndmask_b32_e64 v185, v177, v129, s[8:9]
	v_pk_fma_f32 v[128:129], v[130:131], s[96:97], v[12:13] op_sel_hi:[1,0,0]
	v_cmp_lt_f32_e32 vcc, s33, v130
	v_exp_f32_e32 v128, v128
	v_exp_f32_e32 v129, v129
	v_cvt_pk_bf16_f32 v176, v184, v185
	v_cndmask_b32_e32 v130, 0, v128, vcc
	v_cmp_lt_f32_e32 vcc, s33, v131
	v_cndmask_b32_e64 v186, v128, v130, s[8:9]
	s_nop 0
	v_cndmask_b32_e32 v131, 0, v129, vcc
	v_cndmask_b32_e64 v187, v129, v131, s[8:9]
	v_pk_fma_f32 v[128:129], v[132:133], s[96:97], v[12:13] op_sel_hi:[1,0,0]
	v_cmp_lt_f32_e32 vcc, s33, v132
	v_exp_f32_e32 v128, v128
	v_exp_f32_e32 v129, v129
	v_cvt_pk_bf16_f32 v177, v186, v187
	v_cndmask_b32_e32 v130, 0, v128, vcc
	v_cmp_lt_f32_e32 vcc, s33, v133
	v_cndmask_b32_e64 v188, v128, v130, s[8:9]
	s_nop 0
	v_cndmask_b32_e32 v131, 0, v129, vcc
	v_cndmask_b32_e64 v189, v129, v131, s[8:9]
	v_pk_fma_f32 v[128:129], v[134:135], s[96:97], v[12:13] op_sel_hi:[1,0,0]
	v_cmp_lt_f32_e32 vcc, s33, v134
	v_exp_f32_e32 v128, v128
	v_exp_f32_e32 v129, v129
	v_cvt_pk_bf16_f32 v178, v188, v189
	v_cndmask_b32_e32 v130, 0, v128, vcc
	v_cmp_lt_f32_e32 vcc, s33, v135
	v_cndmask_b32_e64 v134, v128, v130, s[8:9]
	s_nop 0
	v_cndmask_b32_e32 v131, 0, v129, vcc
	v_cndmask_b32_e64 v135, v129, v131, s[8:9]
	s_nop 0
	s_nop 0
	s_nop 0
	s_nop 0
	v_cvt_pk_bf16_f32 v179, v134, v135
	s_nop 0
	v_cmp_lt_f32_e32 vcc, s33, v136
	s_waitcnt lgkmcnt(0)
	v_mfma_f32_32x32x16_bf16 v[96:111], v[216:219], v[176:179], v[96:111]
	s_nop 0
	s_waitcnt lgkmcnt(0)
	v_mfma_f32_32x32x16_bf16 v[80:95], v[220:223], v[176:179], v[80:95]
	v_add_f32_e64 v130, v184, 0
	v_add_f32_e64 v131, v185, 0
	v_add_f32_e64 v130, v186, v130
	v_add_f32_e64 v131, v187, v131
	v_add_f32_e64 v130, v188, v130
	v_add_f32_e64 v131, v189, v131
	v_pk_add_f32 v[176:177], v[134:135], v[130:131]
	v_pk_fma_f32 v[130:131], v[136:137], s[96:97], v[12:13] op_sel_hi:[1,0,0]
	s_nop 0
	v_exp_f32_e32 v130, v130
	v_exp_f32_e32 v131, v131
	v_cndmask_b32_e32 v132, 0, v130, vcc
	v_cmp_lt_f32_e32 vcc, s33, v137
	v_cndmask_b32_e64 v178, v130, v132, s[8:9]
	s_nop 0
	v_cndmask_b32_e32 v133, 0, v131, vcc
	v_cndmask_b32_e64 v179, v131, v133, s[8:9]
	v_pk_fma_f32 v[132:133], v[138:139], s[96:97], v[12:13] op_sel_hi:[1,0,0]
	v_cmp_lt_f32_e32 vcc, s33, v138
	v_exp_f32_e32 v131, v132
	v_exp_f32_e32 v132, v133
	v_cvt_pk_bf16_f32 v130, v178, v179
	v_cndmask_b32_e32 v133, 0, v131, vcc
	v_cmp_lt_f32_e32 vcc, s33, v139
	v_cndmask_b32_e64 v138, v131, v133, s[8:9]
	s_nop 0
	v_cndmask_b32_e32 v134, 0, v132, vcc
	v_cndmask_b32_e64 v139, v132, v134, s[8:9]
	v_pk_fma_f32 v[132:133], v[140:141], s[96:97], v[12:13] op_sel_hi:[1,0,0]
	v_cmp_lt_f32_e32 vcc, s33, v140
	v_exp_f32_e32 v132, v132
	v_exp_f32_e32 v133, v133
	v_cvt_pk_bf16_f32 v131, v138, v139
	v_cndmask_b32_e32 v134, 0, v132, vcc
	v_cmp_lt_f32_e32 vcc, s33, v141
	v_cndmask_b32_e64 v140, v132, v134, s[8:9]
	s_nop 0
	v_cndmask_b32_e32 v135, 0, v133, vcc
	v_cndmask_b32_e64 v141, v133, v135, s[8:9]
	v_pk_fma_f32 v[134:135], v[142:143], s[96:97], v[12:13] op_sel_hi:[1,0,0]
	v_cmp_lt_f32_e32 vcc, s33, v142
	v_exp_f32_e32 v133, v134
	v_exp_f32_e32 v134, v135
	v_cvt_pk_bf16_f32 v132, v140, v141
	v_cndmask_b32_e32 v135, 0, v133, vcc
	v_cmp_lt_f32_e32 vcc, s33, v143
	v_cndmask_b32_e64 v142, v133, v135, s[8:9]
	s_nop 0
	v_cndmask_b32_e32 v136, 0, v134, vcc
	v_cndmask_b32_e64 v143, v134, v136, s[8:9]
	s_nop 0
	v_cvt_pk_bf16_f32 v133, v142, v143
	v_cmp_lt_f32_e32 vcc, s33, v112
	s_nop 0
	v_mfma_f32_32x32x16_bf16 v[96:111], v[224:227], v[130:133], v[96:111]
	s_waitcnt lgkmcnt(0)
	v_mfma_f32_32x32x16_bf16 v[80:95], v[228:231], v[130:133], v[80:95]
	v_fma_f32 v132, v112, s96, v12
	v_fma_f32 v133, v113, s96, v12
	v_fma_f32 v134, v114, s96, v12
	v_fma_f32 v135, v115, s96, v12
	v_exp_f32_e32 v132, v132
	v_exp_f32_e32 v133, v133
	v_pk_add_f32 v[130:131], v[178:179], v[176:177]
	v_cndmask_b32_e32 v112, 0, v132, vcc
	v_cmp_lt_f32_e32 vcc, s33, v113
	v_pk_add_f32 v[130:131], v[138:139], v[130:131]
	v_cndmask_b32_e64 v132, v132, v112, s[8:9]
	v_cndmask_b32_e32 v113, 0, v133, vcc
	v_cndmask_b32_e64 v133, v133, v113, s[8:9]
	v_exp_f32_e32 v113, v134
	v_exp_f32_e32 v134, v135
	v_cmp_lt_f32_e32 vcc, s33, v114
	v_cvt_pk_bf16_f32 v112, v132, v133
	v_pk_add_f32 v[130:131], v[140:141], v[130:131]
	v_cndmask_b32_e32 v114, 0, v113, vcc
	v_cmp_lt_f32_e32 vcc, s33, v115
	v_pk_add_f32 v[130:131], v[142:143], v[130:131]
	s_nop 0
	v_cndmask_b32_e32 v115, 0, v134, vcc
	v_cndmask_b32_e64 v135, v134, v115, s[8:9]
	v_cndmask_b32_e64 v134, v113, v114, s[8:9]
	v_pk_fma_f32 v[114:115], v[116:117], s[96:97], v[12:13] op_sel_hi:[1,0,0]
	v_cmp_lt_f32_e32 vcc, s33, v116
	v_exp_f32_e32 v114, v114
	v_exp_f32_e32 v115, v115
	v_cvt_pk_bf16_f32 v113, v134, v135
	v_cndmask_b32_e32 v116, 0, v114, vcc
	v_cmp_lt_f32_e32 vcc, s33, v117
	v_cndmask_b32_e64 v136, v114, v116, s[8:9]
	s_nop 0
	v_cndmask_b32_e32 v117, 0, v115, vcc
	v_cndmask_b32_e64 v137, v115, v117, s[8:9]
	v_pk_fma_f32 v[116:117], v[118:119], s[96:97], v[12:13] op_sel_hi:[1,0,0]
	v_cmp_lt_f32_e32 vcc, s33, v118
	v_exp_f32_e32 v115, v116
	v_exp_f32_e32 v116, v117
	v_cvt_pk_bf16_f32 v114, v136, v137
	v_cndmask_b32_e32 v117, 0, v115, vcc
	v_cmp_lt_f32_e32 vcc, s33, v119
	v_cndmask_b32_e64 v138, v115, v117, s[8:9]
	s_nop 0
	v_cndmask_b32_e32 v118, 0, v116, vcc
	v_cndmask_b32_e64 v139, v116, v118, s[8:9]
	s_nop 0
	v_cvt_pk_bf16_f32 v115, v138, v139
	v_cmp_lt_f32_e32 vcc, s33, v120
	s_waitcnt lgkmcnt(0)
; #define MFMA(a, b, c) __builtin_amdgcn_mfma_f32_32x32x16_bf16((a), (b), (c), 0, 0, 0)
; template <int N> DI void wait_vmcnt() { asm volatile("s_waitcnt vmcnt(%0)" ::"n"(N) : "memory"); }
;     ...
; #pragma unroll
;       for (int j = 0; j < 4; ++j) {
;         const int i0 = 8 * st + 2 * j;
;         f32x2v t = {S[ks][i0], S[ks][i0 + 1]};
;         t = __builtin_elementwise_fma(t, c2v, mcv);
;         f32x2v pv;
;         if (variant == 1) { pv = t; } else {
;         pv.x = __builtin_amdgcn_exp2f(t.x);
;         pv.y = __builtin_amdgcn_exp2f(t.y);
;         }
;         if (MODE != 0) {
;           if (need_mask) {
;             pv.x = (S[ks][i0] > -1e29f) ? pv.x : 0.f;
;             pv.y = (S[ks][i0 + 1] > -1e29f) ? pv.y : 0.f;
;           }
;         }
;         rs2 += pv;
;         pf.u[j] = __builtin_bit_cast(unsigned, __builtin_convertvector(pv, hwbf16x2));
;       }
; #pragma unroll
;       for (int d = 0; d < DV / 32; ++d) {
;         const char* vp = base + C::KBYTES + (d * 32 + lr) * C::VSTR + (ks * 32 + 16 * st + 4 * lh) * 2;
;         const s16x4 lo = *(const s16x4*)vp, hi = *(const s16x4*)(vp + 16);
;         const bf16x8 vf = __builtin_shufflevector(lo, hi, 0, 1, 2, 3, 4, 5, 6, 7);
;         O[d] = MFMA(vf, pf.v, O[d]);
;       }
;     }
;   float rs = rs2.x + rs2.y;
;   rs += __shfl_xor(rs, 32);
;   l += rs;
;     ...
;   asm volatile("s_waitcnt vmcnt(0)" ::: "memory");
; #pragma unroll
;   for (int t = 0; t < NST - 1; ++t)
;     if (t < ntile) FA_ISSUE(t, t)
;   int stage = 0;
;   for (int t = 0; t < ntile; ++t) {
;     int ahead = ((ntile < t + NST - 1) ? ntile : t + NST - 1) - (t + 1);
;     if (NST == 4 && ahead >= 2) wait_vmcnt<2 * NI>();
;     else if (ahead >= 1) wait_vmcnt<NI>();
;     else wait_vmcnt<0>();
;     raw_barrier();
;     if (t + NST - 1 < ntile) {
;       const int sn = (stage == 0) ? NST - 1 : stage - 1;
;       FA_ISSUE(t + NST - 1, sn)
	v_mfma_f32_32x32x16_bf16 v[96:111], v[232:235], v[112:115], v[96:111]
	s_nop 0
	s_waitcnt lgkmcnt(0)
	v_mfma_f32_32x32x16_bf16 v[80:95], v[236:239], v[112:115], v[80:95]
	v_add_f32_e64 v112, v132, v130
	v_add_f32_e64 v113, v133, v131
	v_add_f32_e64 v112, v134, v112
	v_add_f32_e64 v113, v135, v113
	v_add_f32_e64 v112, v136, v112
	v_add_f32_e64 v113, v137, v113
	v_pk_add_f32 v[130:131], v[138:139], v[112:113]
	v_pk_fma_f32 v[112:113], v[120:121], s[96:97], v[12:13] op_sel_hi:[1,0,0]
	s_nop 0
	v_exp_f32_e32 v112, v112
	v_exp_f32_e32 v113, v113
	v_cndmask_b32_e32 v114, 0, v112, vcc
	v_cmp_lt_f32_e32 vcc, s33, v121
	v_cndmask_b32_e64 v120, v112, v114, s[8:9]
	s_nop 0
	v_cndmask_b32_e32 v115, 0, v113, vcc
	v_cndmask_b32_e64 v121, v113, v115, s[8:9]
	v_pk_fma_f32 v[114:115], v[122:123], s[96:97], v[12:13] op_sel_hi:[1,0,0]
	v_cmp_lt_f32_e32 vcc, s33, v122
	v_exp_f32_e32 v113, v114
	v_exp_f32_e32 v114, v115
	v_cvt_pk_bf16_f32 v112, v120, v121
	v_cndmask_b32_e32 v115, 0, v113, vcc
	v_cmp_lt_f32_e32 vcc, s33, v123
	v_cndmask_b32_e64 v122, v113, v115, s[8:9]
	s_nop 0
	v_cndmask_b32_e32 v116, 0, v114, vcc
	v_cndmask_b32_e64 v123, v114, v116, s[8:9]
	v_pk_fma_f32 v[114:115], v[124:125], s[96:97], v[12:13] op_sel_hi:[1,0,0]
	v_cmp_lt_f32_e32 vcc, s33, v124
	v_exp_f32_e32 v114, v114
	v_exp_f32_e32 v115, v115
	v_cvt_pk_bf16_f32 v113, v122, v123
	v_cndmask_b32_e32 v116, 0, v114, vcc
	v_cmp_lt_f32_e32 vcc, s33, v125
	v_cndmask_b32_e64 v124, v114, v116, s[8:9]
	s_nop 0
	v_cndmask_b32_e32 v117, 0, v115, vcc
	v_cndmask_b32_e64 v125, v115, v117, s[8:9]
	v_pk_fma_f32 v[116:117], v[126:127], s[96:97], v[12:13] op_sel_hi:[1,0,0]
	v_cmp_lt_f32_e32 vcc, s33, v126
	v_exp_f32_e32 v12, v116
	v_exp_f32_e32 v115, v117
	v_cvt_pk_bf16_f32 v114, v124, v125
	v_cndmask_b32_e32 v116, 0, v12, vcc
	v_cmp_lt_f32_e32 vcc, s33, v127
	v_cndmask_b32_e64 v126, v12, v116, s[8:9]
	s_nop 0
	v_cndmask_b32_e32 v117, 0, v115, vcc
	v_cndmask_b32_e64 v127, v115, v117, s[8:9]
	s_nop 0
	v_cvt_pk_bf16_f32 v115, v126, v127
	s_waitcnt lgkmcnt(0)
	s_nop 0
	v_mfma_f32_32x32x16_bf16 v[96:111], v[240:243], v[112:115], v[96:111]
	s_nop 0
	s_waitcnt lgkmcnt(0)
	v_mfma_f32_32x32x16_bf16 v[80:95], v[244:247], v[112:115], v[80:95]
	v_add_f32_e64 v112, v120, v130
	v_add_f32_e64 v113, v121, v131
	v_add_f32_e64 v112, v122, v112
	v_add_f32_e64 v113, v123, v113
	v_add_f32_e64 v112, v124, v112
	v_add_f32_e64 v113, v125, v113
	v_pk_add_f32 v[112:113], v[126:127], v[112:113]
	s_nop 0
	v_add_f32_e32 v12, v112, v113
	ds_bpermute_b32 v112, v165, v12
	s_cmp_ge_i32 s21, s16
	s_cbranch_scc1 .Ldma_m_win2
	s_add_i32 s98, s0, 0xffffb800
	s_cmp_lg_u32 s22, 0
	s_cselect_b32 s98, s98, 0xd800
	s_add_i32 s98, s98, 0
	v_add_u32_e32 v247, s98, v15
	s_nop 0
	v_readfirstlane_b32 s99, v247
	v_add_u32_e32 v247, s98, v13
	s_mov_b32 m0, s99
	v_readfirstlane_b32 s99, v247
	v_add_u32_e32 v247, s98, v169
	global_load_lds_dwordx4 v[10:11], off
	s_mov_b32 m0, s99
	v_readfirstlane_b32 s98, v247
	global_load_lds_dwordx4 v[8:9], off
	s_mov_b32 m0, s98
	s_nop 0
	global_load_lds_dwordx4 v[6:7], off
.Ldma_m_win2:
	s_waitcnt lgkmcnt(0)
	v_add_f32_e32 v12, v12, v112
	v_add_f32_e32 v170, v170, v12
	s_branch .Ldma_skip_win2
; #define MFMA(a, b, c) __builtin_amdgcn_mfma_f32_32x32x16_bf16((a), (b), (c), 0, 0, 0)
; template <int N> DI void wait_vmcnt() { asm volatile("s_waitcnt vmcnt(%0)" ::"n"(N) : "memory"); }
;     ...
;   float mc = m * c2;
;   if (MODE == 2) mc = selbit ? mc : 1e30f;
;   const f32x2v c2v = {c2, c2}, mcv = {-mc, -mc};
;   f32x2v rs2 = {0.f, 0.f};
; #pragma unroll
;   for (int ks = 0; ks < 2; ++ks)
; #pragma unroll
;     for (int st = 0; st < 2; ++st) {
;       union { unsigned u[4]; bf16x8 v; } pf;
; #pragma unroll
;       for (int j = 0; j < 4; ++j) {
;         const int i0 = 8 * st + 2 * j;
;         f32x2v t = {S[ks][i0], S[ks][i0 + 1]};
;         t = __builtin_elementwise_fma(t, c2v, mcv);
;         f32x2v pv;
;         if (variant == 1) { pv = t; } else {
;         pv.x = __builtin_amdgcn_exp2f(t.x);
;         pv.y = __builtin_amdgcn_exp2f(t.y);
;         }
;         if (MODE != 0) {
;           if (need_mask) {
;             pv.x = (S[ks][i0] > -1e29f) ? pv.x : 0.f;
;             pv.y = (S[ks][i0 + 1] > -1e29f) ? pv.y : 0.f;
;           }
;         }
;         rs2 += pv;
;         pf.u[j] = __builtin_bit_cast(unsigned, __builtin_convertvector(pv, hwbf16x2));
;       }
; #pragma unroll
;       for (int d = 0; d < DV / 32; ++d) {
;         const char* vp = base + C::KBYTES + (d * 32 + lr) * C::VSTR + (ks * 32 + 16 * st + 4 * lh) * 2;
;         const s16x4 lo = *(const s16x4*)vp, hi = *(const s16x4*)(vp + 16);
;         const bf16x8 vf = __builtin_shufflevector(lo, hi, 0, 1, 2, 3, 4, 5, 6, 7);
;         O[d] = MFMA(vf, pf.v, O[d]);
;       }
;     }
;   float rs = rs2.x + rs2.y;
;   rs += __shfl_xor(rs, 32);
;     ...
;   asm volatile("s_waitcnt vmcnt(0)" ::: "memory");
; #pragma unroll
;   for (int t = 0; t < NST - 1; ++t)
;     if (t < ntile) FA_ISSUE(t, t)
;   int stage = 0;
;   for (int t = 0; t < ntile; ++t) {
;     int ahead = ((ntile < t + NST - 1) ? ntile : t + NST - 1) - (t + 1);
;     if (NST == 4 && ahead >= 2) wait_vmcnt<2 * NI>();
;     else if (ahead >= 1) wait_vmcnt<NI>();
;     else wait_vmcnt<0>();
;     raw_barrier();
;     if (t + NST - 1 < ntile) {
;       const int sn = (stage == 0) ? NST - 1 : stage - 1;
;       FA_ISSUE(t + NST - 1, sn)
.Lfast_win2:
	v_mul_f32_e32 v12, 0xbe38aa3b, v12
	v_pk_fma_f32 v[176:177], v[128:129], s[96:97], v[12:13] op_sel_hi:[1,0,0]
	v_exp_f32_e32 v184, v176
	v_exp_f32_e32 v185, v177
	v_pk_fma_f32 v[128:129], v[130:131], s[96:97], v[12:13] op_sel_hi:[1,0,0]
	v_exp_f32_e32 v186, v128
	v_exp_f32_e32 v187, v129
	v_cvt_pk_bf16_f32 v176, v184, v185
	v_pk_fma_f32 v[128:129], v[132:133], s[96:97], v[12:13] op_sel_hi:[1,0,0]
	v_exp_f32_e32 v188, v128
	v_exp_f32_e32 v189, v129
	v_cvt_pk_bf16_f32 v177, v186, v187
	v_pk_fma_f32 v[128:129], v[134:135], s[96:97], v[12:13] op_sel_hi:[1,0,0]
	v_exp_f32_e32 v134, v128
	v_exp_f32_e32 v135, v129
	v_cvt_pk_bf16_f32 v178, v188, v189
	v_cvt_pk_bf16_f32 v179, v134, v135
	s_waitcnt lgkmcnt(0)
	s_nop 0
	v_mfma_f32_32x32x16_bf16 v[96:111], v[216:219], v[176:179], v[96:111]
	s_waitcnt lgkmcnt(0)
	v_mfma_f32_32x32x16_bf16 v[80:95], v[220:223], v[176:179], v[80:95]
	v_add_f32_e64 v130, v184, 0
	v_add_f32_e64 v131, v185, 0
	v_add_f32_e64 v130, v186, v130
	v_add_f32_e64 v131, v187, v131
	v_add_f32_e64 v130, v188, v130
	v_add_f32_e64 v131, v189, v131
	v_pk_add_f32 v[176:177], v[134:135], v[130:131]
	v_pk_fma_f32 v[130:131], v[136:137], s[96:97], v[12:13] op_sel_hi:[1,0,0]
	v_exp_f32_e32 v178, v130
	v_exp_f32_e32 v179, v131
	v_pk_fma_f32 v[132:133], v[138:139], s[96:97], v[12:13] op_sel_hi:[1,0,0]
	v_exp_f32_e32 v138, v132
	v_exp_f32_e32 v139, v133
	v_cvt_pk_bf16_f32 v130, v178, v179
	v_pk_fma_f32 v[132:133], v[140:141], s[96:97], v[12:13] op_sel_hi:[1,0,0]
	v_exp_f32_e32 v140, v132
	v_exp_f32_e32 v141, v133
	v_cvt_pk_bf16_f32 v131, v138, v139
	v_pk_fma_f32 v[134:135], v[142:143], s[96:97], v[12:13] op_sel_hi:[1,0,0]
	v_exp_f32_e32 v142, v134
	v_exp_f32_e32 v143, v135
	v_cvt_pk_bf16_f32 v132, v140, v141
	v_cvt_pk_bf16_f32 v133, v142, v143
	s_nop 1
	v_mfma_f32_32x32x16_bf16 v[96:111], v[224:227], v[130:133], v[96:111]
	s_waitcnt lgkmcnt(0)
	v_mfma_f32_32x32x16_bf16 v[80:95], v[228:231], v[130:133], v[80:95]
	v_fma_f32 v132, v112, s96, v12
	v_fma_f32 v133, v113, s96, v12
	v_fma_f32 v134, v114, s96, v12
	v_fma_f32 v135, v115, s96, v12
	v_exp_f32_e32 v132, v132
	v_exp_f32_e32 v133, v133
	v_pk_add_f32 v[130:131], v[178:179], v[176:177]
	v_pk_add_f32 v[130:131], v[138:139], v[130:131]
	v_exp_f32_e32 v134, v134
	v_exp_f32_e32 v135, v135
	v_cvt_pk_bf16_f32 v112, v132, v133
	v_pk_add_f32 v[130:131], v[140:141], v[130:131]
	v_pk_add_f32 v[130:131], v[142:143], v[130:131]
	v_pk_fma_f32 v[114:115], v[116:117], s[96:97], v[12:13] op_sel_hi:[1,0,0]
	v_exp_f32_e32 v136, v114
	v_exp_f32_e32 v137, v115
	v_cvt_pk_bf16_f32 v113, v134, v135
	v_pk_fma_f32 v[116:117], v[118:119], s[96:97], v[12:13] op_sel_hi:[1,0,0]
	v_exp_f32_e32 v138, v116
	v_exp_f32_e32 v139, v117
	v_cvt_pk_bf16_f32 v114, v136, v137
	v_cvt_pk_bf16_f32 v115, v138, v139
	s_waitcnt lgkmcnt(0)
	s_nop 0
	v_mfma_f32_32x32x16_bf16 v[96:111], v[232:235], v[112:115], v[96:111]
	s_waitcnt lgkmcnt(0)
	v_mfma_f32_32x32x16_bf16 v[80:95], v[236:239], v[112:115], v[80:95]
	v_add_f32_e64 v112, v132, v130
	v_add_f32_e64 v113, v133, v131
	v_add_f32_e64 v112, v134, v112
	v_add_f32_e64 v113, v135, v113
	v_add_f32_e64 v112, v136, v112
	v_add_f32_e64 v113, v137, v113
	v_pk_add_f32 v[130:131], v[138:139], v[112:113]
	v_pk_fma_f32 v[112:113], v[120:121], s[96:97], v[12:13] op_sel_hi:[1,0,0]
	v_exp_f32_e32 v120, v112
	v_exp_f32_e32 v121, v113
	v_pk_fma_f32 v[114:115], v[122:123], s[96:97], v[12:13] op_sel_hi:[1,0,0]
	v_exp_f32_e32 v122, v114
	v_exp_f32_e32 v123, v115
	v_cvt_pk_bf16_f32 v112, v120, v121
	v_pk_fma_f32 v[114:115], v[124:125], s[96:97], v[12:13] op_sel_hi:[1,0,0]
	v_exp_f32_e32 v124, v114
	v_exp_f32_e32 v125, v115
	v_cvt_pk_bf16_f32 v113, v122, v123
	v_pk_fma_f32 v[116:117], v[126:127], s[96:97], v[12:13] op_sel_hi:[1,0,0]
	v_exp_f32_e32 v126, v116
	v_exp_f32_e32 v127, v117
	v_cvt_pk_bf16_f32 v114, v124, v125
	v_cvt_pk_bf16_f32 v115, v126, v127
	s_waitcnt lgkmcnt(0)
	s_nop 0
	v_mfma_f32_32x32x16_bf16 v[96:111], v[240:243], v[112:115], v[96:111]
	s_waitcnt lgkmcnt(0)
	v_mfma_f32_32x32x16_bf16 v[80:95], v[244:247], v[112:115], v[80:95]
	v_add_f32_e64 v112, v120, v130
	v_add_f32_e64 v113, v121, v131
	v_add_f32_e64 v112, v122, v112
	v_add_f32_e64 v113, v123, v113
	v_add_f32_e64 v112, v124, v112
	v_add_f32_e64 v113, v125, v113
	v_pk_add_f32 v[112:113], v[126:127], v[112:113]
	v_add_f32_e32 v12, v112, v113
	ds_bpermute_b32 v112, v165, v12
	s_cmp_ge_i32 s21, s16
	s_cbranch_scc1 .Ldma_f_win2
	s_add_i32 s98, s0, 0xffffb800
	s_cmp_lg_u32 s22, 0
	s_cselect_b32 s98, s98, 0xd800
	s_add_i32 s98, s98, 0
	v_add_u32_e32 v247, s98, v15
	s_nop 0
	v_readfirstlane_b32 s99, v247
	v_add_u32_e32 v247, s98, v13
	s_mov_b32 m0, s99
	v_readfirstlane_b32 s99, v247
	v_add_u32_e32 v247, s98, v169
	global_load_lds_dwordx4 v[10:11], off
	s_mov_b32 m0, s99
	v_readfirstlane_b32 s98, v247
	global_load_lds_dwordx4 v[8:9], off
	s_mov_b32 m0, s98
	s_nop 0
	global_load_lds_dwordx4 v[6:7], off
